# scan: k and previous-row r interleaved per column in the LDS operand image (two 16-byte-stride planes), one packed fma per column feeds both row sums; r fetched from the previous row of the chunk
# baseline (speedup 1.0000x reference)
.LBB0_603:
	s_lshl_b32 s0, s33, 4
	s_and_b32 s28, s0, 0x7c0
	s_waitcnt vmcnt(0)
	v_or_b32_e32 v2, s28, v98
	v_lshlrev_b32_e32 v0, 2, v2
	v_lshl_add_u64 v[4:5], s[70:71], 0, v[0:1]
	flat_load_dwordx4 v[42:45], v[4:5]
	v_lshl_add_u64 v[4:5], s[72:73], 0, v[0:1]
	flat_load_dwordx4 v[46:49], v[4:5]
	s_ashr_i32 s14, s33, 7
	s_cmpk_lt_u32 s33, 0x80
	s_cselect_b64 s[12:13], -1, 0
	s_cmpk_gt_u32 s33, 0x7f
	s_cselect_b64 s[88:89], -1, 0
	v_mov_b32_e32 v181, 31
	v_cmp_eq_u32_e64 s[0:1], 0, v131
	s_nop 1
	v_cndmask_b32_e64 v180, -1, v181, s[0:1]
	v_sub_u32_e32 v181, 0, v180
	v_cndmask_b32_e64 v180, v180, v181, s[88:89]
	v_lshlrev_b32_e32 v180, 12, v180
	v_ashrrev_i32_e32 v181, 31, v180
	v_mov_b32_e32 v182, 0xfffff000
	v_mov_b32_e32 v183, 0x1000
	v_cndmask_b32_e64 v182, v182, v183, s[88:89]
	v_ashrrev_i32_e32 v183, 31, v182
	s_and_saveexec_b64 s[4:5], s[8:9]
	s_xor_b64 s[4:5], exec, s[4:5]
	s_lshl_b32 s0, s14, 11
	s_ashr_i32 s1, s0, 31
	s_or_saveexec_b64 s[16:17], s[4:5]
	s_and_b32 s4, s33, 3
	v_mov_b64_e32 v[4:5], s[0:1]
	v_lshlrev_b32_e32 v2, 1, v2
	s_xor_b64 exec, exec, s[16:17]
	s_cbranch_execz .LBB0_615
	v_cndmask_b32_e64 v4, v138, v137, s[12:13]
	v_lshlrev_b32_e32 v6, 13, v4
	v_mov_b32_e32 v7, v1
	v_lshlrev_b32_e32 v12, 14, v4
	v_mov_b32_e32 v13, v1
	s_lshl_b32 s18, s14, 11
	v_lshl_add_u64 v[8:9], s[48:49], 0, v[6:7]
	v_lshl_add_u64 v[12:13], s[60:61], 0, v[12:13]
	s_ashr_i32 s19, s18, 31
	v_lshl_add_u64 v[6:7], s[52:53], 0, v[6:7]
	v_lshl_add_u64 v[8:9], v[8:9], 0, v[0:1]
	v_lshlrev_b32_e32 v10, 12, v4
	v_mov_b32_e32 v11, v1
	v_lshl_add_u64 v[12:13], s[18:19], 2, v[12:13]
	v_lshl_add_u64 v[6:7], s[18:19], 1, v[6:7]
	v_mov_b32_e32 v3, v1
	v_lshl_add_u64 v[12:13], v[12:13], 0, v[0:1]
	global_load_dwordx4 v[34:37], v[8:9], off
	global_load_dwordx4 v[38:41], v[12:13], off
	v_lshl_add_u64 v[6:7], v[6:7], 0, v[2:3]
	v_lshl_add_u64 v[8:9], s[66:67], 0, v[10:11]
	v_lshl_add_u64 v[8:9], v[8:9], 0, v[2:3]
	global_load_dwordx2 v[110:111], v[6:7], off
	v_lshl_add_u64 v[8:9], v[8:9], 0, v[180:181]
	global_load_dwordx2 v[112:113], v[8:9], off
	s_and_saveexec_b64 s[0:1], s[10:11]
	s_cbranch_execz .LBB0_608
	v_lshlrev_b32_e32 v4, 11, v4
	v_lshlrev_b32_e32 v4, 1, v4
	v_mov_b32_e32 v5, v1
	v_lshl_add_u64 v[4:5], s[68:69], 0, v[4:5]
	s_lshl_b32 s86, s28, 1
	v_lshl_add_u64 v[4:5], v[4:5], 0, s[86:87]
	s_lshl_b32 s86, s4, 5
	v_lshl_add_u64 v[4:5], v[4:5], 0, s[86:87]
	v_lshlrev_b32_e32 v6, 1, v98
	v_mov_b32_e32 v7, v1
	v_lshl_add_u64 v[4:5], v[4:5], 0, v[6:7]
	global_load_dwordx2 v[106:107], v[4:5], off
.LBB0_608:
	s_or_b64 exec, exec, s[0:1]
	v_cndmask_b32_e64 v4, v140, v139, s[12:13]
	v_lshlrev_b32_e32 v6, 13, v4
	v_mov_b32_e32 v7, v1
	v_lshlrev_b32_e32 v12, 14, v4
	v_mov_b32_e32 v13, v1
	v_lshl_add_u64 v[8:9], s[48:49], 0, v[6:7]
	v_lshl_add_u64 v[12:13], s[60:61], 0, v[12:13]
	v_lshl_add_u64 v[6:7], s[52:53], 0, v[6:7]
	v_lshl_add_u64 v[8:9], v[8:9], 0, v[0:1]
	v_lshlrev_b32_e32 v10, 12, v4
	v_mov_b32_e32 v11, v1
	v_lshl_add_u64 v[12:13], s[18:19], 2, v[12:13]
	v_lshl_add_u64 v[6:7], s[18:19], 1, v[6:7]
	v_lshl_add_u64 v[12:13], v[12:13], 0, v[0:1]
	global_load_dwordx4 v[50:53], v[8:9], off
	global_load_dwordx4 v[54:57], v[12:13], off
	v_lshl_add_u64 v[6:7], v[6:7], 0, v[2:3]
	v_lshl_add_u64 v[8:9], s[66:67], 0, v[10:11]
	v_lshl_add_u64 v[8:9], v[8:9], 0, v[2:3]
	global_load_dwordx2 v[114:115], v[6:7], off
	v_lshl_add_u64 v[8:9], v[8:9], 0, v[182:183]
	global_load_dwordx2 v[116:117], v[8:9], off
	s_and_saveexec_b64 s[0:1], s[10:11]
	s_cbranch_execz .LBB0_610
	v_lshlrev_b32_e32 v3, 11, v4
	v_lshlrev_b32_e32 v4, 1, v3
	v_mov_b32_e32 v5, v1
	v_lshl_add_u64 v[4:5], s[68:69], 0, v[4:5]
	s_lshl_b32 s86, s28, 1
	v_lshl_add_u64 v[4:5], v[4:5], 0, s[86:87]
	s_lshl_b32 s86, s4, 5
	v_lshl_add_u64 v[4:5], v[4:5], 0, s[86:87]
	v_lshlrev_b32_e32 v6, 1, v98
	v_mov_b32_e32 v7, v1
	v_lshl_add_u64 v[4:5], v[4:5], 0, v[6:7]
	global_load_dwordx2 v[108:109], v[4:5], off
.LBB0_610:
	s_or_b64 exec, exec, s[0:1]
	s_waitcnt vmcnt(0) lgkmcnt(0)
	v_pk_mul_f32 v[8:9], v[42:43], v[34:35]
	v_pk_mul_f32 v[4:5], v[44:45], v[36:37]
	v_pk_mul_f32 v[10:11], v[8:9], v[8:9]
	v_pk_mul_f32 v[6:7], v[4:5], v[4:5]
	v_add_f32_e32 v3, v10, v11
	v_add_f32_e32 v3, v6, v3
	v_add_f32_e32 v3, v7, v3
	v_and_b32_e32 v13, 0xffff0000, v110
	v_lshlrev_b32_e32 v14, 16, v111
	v_add_f32_dpp v3, v3, v3 quad_perm:[1,0,3,2] row_mask:0xf bank_mask:0xf bound_ctrl:1
	v_and_b32_e32 v15, 0xffff0000, v111
	v_lshlrev_b32_e32 v18, 16, v113
	v_add_f32_dpp v3, v3, v3 quad_perm:[2,3,0,1] row_mask:0xf bank_mask:0xf bound_ctrl:1
	v_and_b32_e32 v19, 0xffff0000, v113
	s_nop 0
	v_add_f32_dpp v3, v3, v3 row_half_mirror row_mask:0xf bank_mask:0xf bound_ctrl:1
	s_nop 1
	v_add_f32_dpp v3, v3, v3 row_ror:8 row_mask:0xf bank_mask:0xf bound_ctrl:1
	v_mul_f32_e32 v6, 0x4f800000, v3
	v_cmp_gt_f32_e32 vcc, s74, v3
	s_nop 1
	v_cndmask_b32_e32 v3, v3, v6, vcc
	v_sqrt_f32_e32 v6, v3
	s_nop 0
	v_add_u32_e32 v7, -1, v6
	v_fma_f32 v10, -v7, v6, v3
	v_cmp_ge_f32_e64 s[14:15], 0, v10
	v_add_u32_e32 v10, 1, v6
	s_nop 0
	v_cndmask_b32_e64 v7, v6, v7, s[14:15]
	v_fma_f32 v6, -v10, v6, v3
	v_cmp_lt_f32_e64 s[14:15], 0, v6
	s_nop 1
	v_cndmask_b32_e64 v6, v7, v10, s[14:15]
	v_mul_f32_e32 v7, 0x37800000, v6
	v_cndmask_b32_e32 v6, v6, v7, vcc
	v_cmp_class_f32_e32 vcc, v3, v163
	s_nop 1
	v_cndmask_b32_e32 v3, v6, v3, vcc
	v_max_f32_e32 v3, 0x2b8cbccc, v3
	v_div_scale_f32 v6, s[0:1], v3, v3, 1.0
	v_rcp_f32_e32 v7, v6
	s_nop 0
	v_fma_f32 v10, -v6, v7, 1.0
	v_fmac_f32_e32 v7, v10, v7
	v_div_scale_f32 v10, vcc, 1.0, v3, 1.0
	v_mul_f32_e32 v11, v10, v7
	v_fma_f32 v12, -v6, v11, v10
	v_fmac_f32_e32 v11, v12, v7
	v_fma_f32 v6, -v6, v11, v10
	v_div_fmas_f32 v6, v6, v7, v11
	v_div_fixup_f32 v10, v6, v3, 1.0
	v_lshlrev_b32_e32 v12, 16, v110
	v_pk_mul_f32 v[6:7], v[4:5], v[10:11] op_sel_hi:[1,0]
	v_pk_mul_f32 v[4:5], v[8:9], v[10:11] op_sel_hi:[1,0]
	v_pk_add_f32 v[8:9], v[14:15], -1.0 op_sel_hi:[1,0]
	v_pk_add_f32 v[10:11], v[12:13], -1.0 op_sel_hi:[1,0]
	v_pk_fma_f32 v[8:9], v[48:49], v[8:9], 1.0 op_sel_hi:[1,1,0]
	v_pk_fma_f32 v[16:17], v[46:47], v[10:11], 1.0 op_sel_hi:[1,1,0]
	v_pk_mul_f32 v[10:11], v[36:37], v[8:9]
	v_pk_mul_f32 v[8:9], v[34:35], v[16:17]
	v_pk_mul_f32 v[14:15], v[6:7], v[14:15]
	v_pk_mul_f32 v[12:13], v[4:5], v[12:13]
	v_lshlrev_b32_e32 v16, 16, v112
	v_and_b32_e32 v17, 0xffff0000, v112
	v_mov_b32_e32 v172, v4
	v_mov_b32_e32 v173, v16
	v_mov_b32_e32 v174, v5
	v_mov_b32_e32 v175, v17
	v_mov_b32_e32 v176, v6
	v_mov_b32_e32 v177, v18
	v_mov_b32_e32 v178, v7
	v_mov_b32_e32 v179, v19
	ds_write_b128 v141, v[172:175]
	ds_write_b128 v141, v[176:179] offset:8192
	ds_write_b128 v141, v[38:41] offset:32768
	ds_write_b128 v141, v[12:15] offset:16384
	ds_write_b128 v141, v[8:11] offset:24576
	s_and_saveexec_b64 s[0:1], s[10:11]
	v_lshlrev_b32_e32 v4, 16, v106
	v_and_b32_e32 v5, 0xffff0000, v106
	v_lshlrev_b32_e32 v6, 16, v107
	v_and_b32_e32 v7, 0xffff0000, v107
	ds_write_b128 v143, v[4:7] offset:40960
	s_or_b64 exec, exec, s[0:1]
	v_pk_mul_f32 v[8:9], v[42:43], v[50:51]
	v_pk_mul_f32 v[4:5], v[44:45], v[52:53]
	v_pk_mul_f32 v[10:11], v[8:9], v[8:9]
	v_pk_mul_f32 v[6:7], v[4:5], v[4:5]
	v_add_f32_e32 v3, v10, v11
	v_add_f32_e32 v3, v6, v3
	v_add_f32_e32 v3, v7, v3
	v_and_b32_e32 v13, 0xffff0000, v114
	v_lshlrev_b32_e32 v14, 16, v115
	v_add_f32_dpp v3, v3, v3 quad_perm:[1,0,3,2] row_mask:0xf bank_mask:0xf bound_ctrl:1
	v_and_b32_e32 v15, 0xffff0000, v115
	v_lshlrev_b32_e32 v18, 16, v117
	v_add_f32_dpp v3, v3, v3 quad_perm:[2,3,0,1] row_mask:0xf bank_mask:0xf bound_ctrl:1
	v_and_b32_e32 v19, 0xffff0000, v117
	s_nop 0
	v_add_f32_dpp v3, v3, v3 row_half_mirror row_mask:0xf bank_mask:0xf bound_ctrl:1
	s_nop 1
	v_add_f32_dpp v3, v3, v3 row_ror:8 row_mask:0xf bank_mask:0xf bound_ctrl:1
	v_mul_f32_e32 v6, 0x4f800000, v3
	v_cmp_gt_f32_e32 vcc, s74, v3
	s_nop 1
	v_cndmask_b32_e32 v3, v3, v6, vcc
	v_sqrt_f32_e32 v6, v3
	s_nop 0
	v_add_u32_e32 v7, -1, v6
	v_fma_f32 v10, -v7, v6, v3
	v_cmp_ge_f32_e64 s[14:15], 0, v10
	v_add_u32_e32 v10, 1, v6
	s_nop 0
	v_cndmask_b32_e64 v7, v6, v7, s[14:15]
	v_fma_f32 v6, -v10, v6, v3
	v_cmp_lt_f32_e64 s[14:15], 0, v6
	s_nop 1
	v_cndmask_b32_e64 v6, v7, v10, s[14:15]
	v_mul_f32_e32 v7, 0x37800000, v6
	v_cndmask_b32_e32 v6, v6, v7, vcc
	v_cmp_class_f32_e32 vcc, v3, v163
	s_nop 1
	v_cndmask_b32_e32 v3, v6, v3, vcc
	v_max_f32_e32 v3, 0x2b8cbccc, v3
	v_div_scale_f32 v6, s[0:1], v3, v3, 1.0
	v_rcp_f32_e32 v7, v6
	s_nop 0
	v_fma_f32 v10, -v6, v7, 1.0
	v_fmac_f32_e32 v7, v10, v7
	v_div_scale_f32 v10, vcc, 1.0, v3, 1.0
	v_mul_f32_e32 v11, v10, v7
	v_fma_f32 v12, -v6, v11, v10
	v_fmac_f32_e32 v11, v12, v7
	v_fma_f32 v6, -v6, v11, v10
	v_div_fmas_f32 v6, v6, v7, v11
	v_div_fixup_f32 v10, v6, v3, 1.0
	v_lshlrev_b32_e32 v12, 16, v114
	v_pk_mul_f32 v[6:7], v[4:5], v[10:11] op_sel_hi:[1,0]
	v_pk_mul_f32 v[4:5], v[8:9], v[10:11] op_sel_hi:[1,0]
	v_pk_add_f32 v[8:9], v[14:15], -1.0 op_sel_hi:[1,0]
	v_pk_add_f32 v[10:11], v[12:13], -1.0 op_sel_hi:[1,0]
	v_pk_fma_f32 v[8:9], v[48:49], v[8:9], 1.0 op_sel_hi:[1,1,0]
	v_pk_fma_f32 v[16:17], v[46:47], v[10:11], 1.0 op_sel_hi:[1,1,0]
	v_pk_mul_f32 v[10:11], v[52:53], v[8:9]
	v_pk_mul_f32 v[8:9], v[50:51], v[16:17]
	v_pk_mul_f32 v[14:15], v[6:7], v[14:15]
	v_pk_mul_f32 v[12:13], v[4:5], v[12:13]
	v_lshlrev_b32_e32 v16, 16, v116
	v_and_b32_e32 v17, 0xffff0000, v116
	v_mov_b32_e32 v172, v4
	v_mov_b32_e32 v173, v16
	v_mov_b32_e32 v174, v5
	v_mov_b32_e32 v175, v17
	v_mov_b32_e32 v176, v6
	v_mov_b32_e32 v177, v18
	v_mov_b32_e32 v178, v7
	v_mov_b32_e32 v179, v19
	ds_write_b128 v145, v[172:175]
	ds_write_b128 v145, v[176:179] offset:8192
	ds_write_b128 v145, v[54:57] offset:32768
	ds_write_b128 v145, v[12:15] offset:16384
	ds_write_b128 v145, v[8:11] offset:24576
	s_and_saveexec_b64 s[0:1], s[10:11]
	v_lshlrev_b32_e32 v4, 16, v108
	v_and_b32_e32 v5, 0xffff0000, v108
	v_lshlrev_b32_e32 v6, 16, v109
	v_and_b32_e32 v7, 0xffff0000, v109
	ds_write_b128 v146, v[4:7] offset:40960
	s_or_b64 exec, exec, s[0:1]
	v_mov_b64_e32 v[4:5], s[18:19]

.Lscan_pro_639:
	s_or_b64 exec, exec, s[0:1]
	v_ashrrev_i32_e32 v51, 31, v50
	v_lshlrev_b64 v[52:53], 13, v[50:51]
	v_lshlrev_b64 v[36:37], 14, v[50:51]
	v_lshl_add_u64 v[34:35], v[120:121], 0, v[52:53]
	v_lshlrev_b64 v[54:55], 12, v[50:51]
	v_lshl_add_u64 v[38:39], v[122:123], 0, v[36:37]
	v_lshl_add_u64 v[52:53], v[124:125], 0, v[52:53]
	global_load_dwordx4 v[34:37], v[34:35], off
	s_nop 0
	global_load_dwordx4 v[38:41], v[38:39], off
	v_lshl_add_u64 v[54:55], v[126:127], 0, v[54:55]
	global_load_dwordx2 v[110:111], v[52:53], off
	v_lshl_add_u64 v[54:55], v[54:55], 0, v[180:181]
	global_load_dwordx2 v[112:113], v[54:55], off
	s_and_saveexec_b64 s[0:1], s[10:11]
	s_cbranch_execz .Lscan_pro_641
	v_lshlrev_b64 v[50:51], 11, v[50:51]
	v_lshl_add_u64 v[50:51], v[50:51], 1, v[128:129]
	global_load_dwordx2 v[106:107], v[50:51], off

.Lscan_pro_652:
	s_or_b64 exec, exec, s[0:1]
	v_ashrrev_i32_e32 v59, 31, v58
	v_lshlrev_b64 v[62:63], 13, v[58:59]
	v_lshlrev_b64 v[52:53], 14, v[58:59]
	v_lshl_add_u64 v[50:51], v[120:121], 0, v[62:63]
	v_lshlrev_b64 v[66:67], 12, v[58:59]
	v_lshl_add_u64 v[54:55], v[122:123], 0, v[52:53]
	v_lshl_add_u64 v[62:63], v[124:125], 0, v[62:63]
	global_load_dwordx4 v[50:53], v[50:51], off
	s_nop 0
	global_load_dwordx4 v[54:57], v[54:55], off
	v_lshl_add_u64 v[66:67], v[126:127], 0, v[66:67]
	global_load_dwordx2 v[114:115], v[62:63], off
	v_lshl_add_u64 v[66:67], v[66:67], 0, v[182:183]
	global_load_dwordx2 v[116:117], v[66:67], off
	s_and_saveexec_b64 s[0:1], s[10:11]
	s_cbranch_execz .Lscan_pro_654
	v_lshlrev_b64 v[58:59], 11, v[58:59]
	v_lshl_add_u64 v[58:59], v[58:59], 1, v[128:129]
	global_load_dwordx2 v[108:109], v[58:59], off
.Lscan_pro_654:
	s_or_b64 exec, exec, s[0:1]
	v_mov_b32_e32 v59, 0
	v_add_u32_e32 v0, 64, v131
	v_sub_u32_e32 v58, 0x20ff, v0
	v_or_b32_e32 v0, 0x2000, v0
	v_cndmask_b32_e64 v58, v0, v58, s[88:89]
	v_lshlrev_b64 v[60:61], 12, v[58:59]
	v_lshlrev_b64 v[62:63], 13, v[58:59]
	v_lshlrev_b64 v[66:67], 14, v[58:59]
	v_lshl_add_u64 v[78:79], v[62:63], 0, v[120:121]
	v_lshl_add_u64 v[80:81], v[66:67], 0, v[122:123]
	v_lshl_add_u64 v[82:83], v[62:63], 0, v[124:125]
	v_lshl_add_u64 v[84:85], v[60:61], 0, v[126:127]
	v_lshl_add_u64 v[84:85], v[84:85], 0, v[180:181]
	v_lshl_add_u64 v[86:87], v[60:61], 0, v[128:129]
	v_add_u32_e32 v0, 64, v136
	v_sub_u32_e32 v58, 0x20ff, v0
	v_or_b32_e32 v0, 0x2000, v0
	v_cndmask_b32_e64 v58, v0, v58, s[88:89]
	v_lshlrev_b64 v[60:61], 12, v[58:59]
	v_lshlrev_b64 v[62:63], 13, v[58:59]
	v_lshlrev_b64 v[66:67], 14, v[58:59]
	v_lshl_add_u64 v[88:89], v[62:63], 0, v[120:121]
	v_lshl_add_u64 v[90:91], v[66:67], 0, v[122:123]
	v_lshl_add_u64 v[92:93], v[62:63], 0, v[124:125]
	v_lshl_add_u64 v[94:95], v[60:61], 0, v[126:127]
	v_lshl_add_u64 v[94:95], v[94:95], 0, v[182:183]
	v_lshl_add_u64 v[96:97], v[60:61], 0, v[128:129]

.LBB0_619:
	s_and_saveexec_b64 s[0:1], s[8:9]
	s_xor_b64 s[14:15], exec, s[0:1]
	s_cbranch_execz .LBB0_623
	v_and_b32_e32 v87, 1, v101
	v_mad_u32_u24 v0, v87, s75, 0
	v_lshl_add_u32 v84, v98, 2, v0
	v_lshl_add_u32 v85, v99, 2, v0
	v_lshl_add_u32 v86, v87, 14, v162
	ds_read_b128 v[2:5], v84 offset:0
	ds_read_b128 v[14:17], v84 offset:24576
	ds_read_b32 v22, v85 offset:40960
	ds_read_b128 v[18:21], v84 offset:8192
	ds_read_b128 v[6:9], v84 offset:32768
	ds_read_b128 v[10:13], v84 offset:16384
	ds_read_b128 v[24:27], v84 offset:256
	ds_read_b128 v[36:39], v84 offset:24832
	ds_read_b32 v44, v85 offset:41024
	ds_read_b128 v[40:43], v84 offset:8448
	ds_read_b128 v[28:31], v84 offset:33024
	ds_read_b128 v[32:35], v84 offset:16640
	v_add_u32_e32 v86, 0x15000, v86
	s_waitcnt lgkmcnt(6)
	v_pk_mul_f32 v[68:69], v[2:3], v[78:79] op_sel_hi:[1,0]
	v_pk_mul_f32 v[70:71], v[22:23], v[14:15] op_sel_hi:[0,1]
	v_pk_fma_f32 v[68:69], v[4:5], v[78:79], v[68:69] op_sel:[0,1,0]
	v_pk_mul_f32 v[72:73], v[22:23], v[16:17] op_sel_hi:[0,1]
	v_pk_fma_f32 v[68:69], v[18:19], v[80:81], v[68:69] op_sel_hi:[1,0,1]
	v_pk_fma_f32 v[74:75], v[6:7], v[78:79], v[70:71]
	v_pk_fma_f32 v[68:69], v[20:21], v[80:81], v[68:69] op_sel:[0,1,0]
	v_pk_fma_f32 v[76:77], v[8:9], v[80:81], v[72:73]
	ds_read_b128 v[46:49], v84 offset:512
	v_add_f32_dpp v68, v68, v68 quad_perm:[1,0,3,2] row_mask:0xf bank_mask:0xf bound_ctrl:1
	ds_read_b128 v[58:61], v84 offset:25088
	ds_read_b32 v66, v85 offset:41088
	v_add_f32_dpp v68, v68, v68 quad_perm:[2,3,0,1] row_mask:0xf bank_mask:0xf bound_ctrl:1
	ds_read_b128 v[62:65], v84 offset:8704
	ds_read_b128 v[50:53], v84 offset:33280
	v_add_f32_dpp v68, v68, v68 row_half_mirror row_mask:0xf bank_mask:0xf bound_ctrl:1
	ds_read_b128 v[54:57], v84 offset:16896
	s_nop 0
	v_add_f32_dpp v68, v68, v68 row_ror:8 row_mask:0xf bank_mask:0xf bound_ctrl:1
	v_pk_fma_f32 v[78:79], v[10:11], v[68:69], v[74:75] op_sel_hi:[1,0,1] neg_lo:[0,1,0] neg_hi:[0,1,0]
	v_pk_fma_f32 v[80:81], v[12:13], v[68:69], v[76:77] op_sel_hi:[1,0,1] neg_lo:[0,1,0] neg_hi:[0,1,0]
	s_waitcnt lgkmcnt(6)
	v_pk_mul_f32 v[68:69], v[24:25], v[78:79] op_sel_hi:[1,0]
	v_pk_mul_f32 v[70:71], v[44:45], v[36:37] op_sel_hi:[0,1]
	v_pk_fma_f32 v[68:69], v[26:27], v[78:79], v[68:69] op_sel:[0,1,0]
	v_pk_mul_f32 v[72:73], v[44:45], v[38:39] op_sel_hi:[0,1]
	v_pk_fma_f32 v[68:69], v[40:41], v[80:81], v[68:69] op_sel_hi:[1,0,1]
	v_pk_fma_f32 v[74:75], v[28:29], v[78:79], v[70:71]
	v_pk_fma_f32 v[68:69], v[42:43], v[80:81], v[68:69] op_sel:[0,1,0]
	v_pk_fma_f32 v[76:77], v[30:31], v[80:81], v[72:73]
	ds_read_b128 v[106:109], v84 offset:768
	v_add_f32_dpp v68, v68, v68 quad_perm:[1,0,3,2] row_mask:0xf bank_mask:0xf bound_ctrl:1
	ds_read_b128 v[118:121], v84 offset:25344
	v_add_f32_dpp v82, v69, v69 row_ror:8 row_mask:0xf bank_mask:0xf bound_ctrl:1
	v_add_f32_dpp v68, v68, v68 quad_perm:[2,3,0,1] row_mask:0xf bank_mask:0xf bound_ctrl:1
	ds_read_b32 v126, v85 offset:41152
	ds_read_b128 v[122:125], v84 offset:8960
	v_add_f32_dpp v68, v68, v68 row_half_mirror row_mask:0xf bank_mask:0xf bound_ctrl:1
	ds_read_b128 v[110:113], v84 offset:33536
	ds_read_b128 v[114:117], v84 offset:17152
	v_add_f32_dpp v68, v68, v68 row_ror:8 row_mask:0xf bank_mask:0xf bound_ctrl:1
	v_pk_fma_f32 v[78:79], v[32:33], v[68:69], v[74:75] op_sel_hi:[1,0,1] neg_lo:[0,1,0] neg_hi:[0,1,0]
	v_pk_fma_f32 v[80:81], v[34:35], v[68:69], v[76:77] op_sel_hi:[1,0,1] neg_lo:[0,1,0] neg_hi:[0,1,0]
	s_waitcnt lgkmcnt(6)
	v_pk_mul_f32 v[68:69], v[46:47], v[78:79] op_sel_hi:[1,0]
	v_pk_mul_f32 v[70:71], v[66:67], v[58:59] op_sel_hi:[0,1]
	v_pk_fma_f32 v[68:69], v[48:49], v[78:79], v[68:69] op_sel:[0,1,0]
	v_pk_mul_f32 v[72:73], v[66:67], v[60:61] op_sel_hi:[0,1]
	v_pk_fma_f32 v[68:69], v[62:63], v[80:81], v[68:69] op_sel_hi:[1,0,1]
	v_pk_fma_f32 v[74:75], v[50:51], v[78:79], v[70:71]
	v_pk_fma_f32 v[68:69], v[64:65], v[80:81], v[68:69] op_sel:[0,1,0]
	v_pk_fma_f32 v[76:77], v[52:53], v[80:81], v[72:73]
	ds_read_b128 v[2:5], v84 offset:1024
	v_add_f32_dpp v68, v68, v68 quad_perm:[1,0,3,2] row_mask:0xf bank_mask:0xf bound_ctrl:1
	ds_read_b128 v[14:17], v84 offset:25600
	v_add_f32_dpp v88, v69, v69 row_ror:8 row_mask:0xf bank_mask:0xf bound_ctrl:1
	v_add_f32_dpp v68, v68, v68 quad_perm:[2,3,0,1] row_mask:0xf bank_mask:0xf bound_ctrl:1
	ds_write2st64_b32 v86, v82, v88 offset0:0 offset1:2
	ds_read_b32 v22, v85 offset:41216
	v_add_f32_dpp v68, v68, v68 row_half_mirror row_mask:0xf bank_mask:0xf bound_ctrl:1
	ds_read_b128 v[18:21], v84 offset:9216
	ds_read_b128 v[6:9], v84 offset:33792
	v_add_f32_dpp v68, v68, v68 row_ror:8 row_mask:0xf bank_mask:0xf bound_ctrl:1
	ds_read_b128 v[10:13], v84 offset:17408
	v_pk_fma_f32 v[78:79], v[54:55], v[68:69], v[74:75] op_sel_hi:[1,0,1] neg_lo:[0,1,0] neg_hi:[0,1,0]
	v_pk_fma_f32 v[80:81], v[56:57], v[68:69], v[76:77] op_sel_hi:[1,0,1] neg_lo:[0,1,0] neg_hi:[0,1,0]
	s_waitcnt lgkmcnt(7)
	v_pk_mul_f32 v[68:69], v[106:107], v[78:79] op_sel_hi:[1,0]
	v_pk_mul_f32 v[70:71], v[126:127], v[118:119] op_sel_hi:[0,1]
	v_pk_fma_f32 v[68:69], v[108:109], v[78:79], v[68:69] op_sel:[0,1,0]
	v_pk_mul_f32 v[72:73], v[126:127], v[120:121] op_sel_hi:[0,1]
	v_pk_fma_f32 v[68:69], v[122:123], v[80:81], v[68:69] op_sel_hi:[1,0,1]
	v_pk_fma_f32 v[74:75], v[110:111], v[78:79], v[70:71]
	v_pk_fma_f32 v[68:69], v[124:125], v[80:81], v[68:69] op_sel:[0,1,0]
	v_pk_fma_f32 v[76:77], v[112:113], v[80:81], v[72:73]
	ds_read_b128 v[24:27], v84 offset:1280
	v_add_f32_dpp v68, v68, v68 quad_perm:[1,0,3,2] row_mask:0xf bank_mask:0xf bound_ctrl:1
	ds_read_b128 v[36:39], v84 offset:25856
	v_add_f32_dpp v82, v69, v69 row_ror:8 row_mask:0xf bank_mask:0xf bound_ctrl:1
	v_add_f32_dpp v68, v68, v68 quad_perm:[2,3,0,1] row_mask:0xf bank_mask:0xf bound_ctrl:1
	ds_read_b32 v44, v85 offset:41280
	ds_read_b128 v[40:43], v84 offset:9472
	v_add_f32_dpp v68, v68, v68 row_half_mirror row_mask:0xf bank_mask:0xf bound_ctrl:1
	ds_read_b128 v[28:31], v84 offset:34048
	ds_read_b128 v[32:35], v84 offset:17664
	v_add_f32_dpp v68, v68, v68 row_ror:8 row_mask:0xf bank_mask:0xf bound_ctrl:1
	v_pk_fma_f32 v[78:79], v[114:115], v[68:69], v[74:75] op_sel_hi:[1,0,1] neg_lo:[0,1,0] neg_hi:[0,1,0]
	v_pk_fma_f32 v[80:81], v[116:117], v[68:69], v[76:77] op_sel_hi:[1,0,1] neg_lo:[0,1,0] neg_hi:[0,1,0]
	s_waitcnt lgkmcnt(6)
	v_pk_mul_f32 v[68:69], v[2:3], v[78:79] op_sel_hi:[1,0]
	v_pk_mul_f32 v[70:71], v[22:23], v[14:15] op_sel_hi:[0,1]
	v_pk_fma_f32 v[68:69], v[4:5], v[78:79], v[68:69] op_sel:[0,1,0]
	v_pk_mul_f32 v[72:73], v[22:23], v[16:17] op_sel_hi:[0,1]
	v_pk_fma_f32 v[68:69], v[18:19], v[80:81], v[68:69] op_sel_hi:[1,0,1]
	v_pk_fma_f32 v[74:75], v[6:7], v[78:79], v[70:71]
	v_pk_fma_f32 v[68:69], v[20:21], v[80:81], v[68:69] op_sel:[0,1,0]
	v_pk_fma_f32 v[76:77], v[8:9], v[80:81], v[72:73]
	ds_read_b128 v[46:49], v84 offset:1536
	v_add_f32_dpp v68, v68, v68 quad_perm:[1,0,3,2] row_mask:0xf bank_mask:0xf bound_ctrl:1
	ds_read_b128 v[58:61], v84 offset:26112
	v_add_f32_dpp v88, v69, v69 row_ror:8 row_mask:0xf bank_mask:0xf bound_ctrl:1
	v_add_f32_dpp v68, v68, v68 quad_perm:[2,3,0,1] row_mask:0xf bank_mask:0xf bound_ctrl:1
	ds_write2st64_b32 v86, v82, v88 offset0:4 offset1:6
	ds_read_b32 v66, v85 offset:41344
	v_add_f32_dpp v68, v68, v68 row_half_mirror row_mask:0xf bank_mask:0xf bound_ctrl:1
	ds_read_b128 v[62:65], v84 offset:9728
	ds_read_b128 v[50:53], v84 offset:34304
	v_add_f32_dpp v68, v68, v68 row_ror:8 row_mask:0xf bank_mask:0xf bound_ctrl:1
	ds_read_b128 v[54:57], v84 offset:17920
	v_pk_fma_f32 v[78:79], v[10:11], v[68:69], v[74:75] op_sel_hi:[1,0,1] neg_lo:[0,1,0] neg_hi:[0,1,0]
	v_pk_fma_f32 v[80:81], v[12:13], v[68:69], v[76:77] op_sel_hi:[1,0,1] neg_lo:[0,1,0] neg_hi:[0,1,0]
	s_waitcnt lgkmcnt(7)
	v_pk_mul_f32 v[68:69], v[24:25], v[78:79] op_sel_hi:[1,0]
	v_pk_mul_f32 v[70:71], v[44:45], v[36:37] op_sel_hi:[0,1]
	v_pk_fma_f32 v[68:69], v[26:27], v[78:79], v[68:69] op_sel:[0,1,0]
	v_pk_mul_f32 v[72:73], v[44:45], v[38:39] op_sel_hi:[0,1]
	v_pk_fma_f32 v[68:69], v[40:41], v[80:81], v[68:69] op_sel_hi:[1,0,1]
	v_pk_fma_f32 v[74:75], v[28:29], v[78:79], v[70:71]
	v_pk_fma_f32 v[68:69], v[42:43], v[80:81], v[68:69] op_sel:[0,1,0]
	v_pk_fma_f32 v[76:77], v[30:31], v[80:81], v[72:73]
	ds_read_b128 v[106:109], v84 offset:1792
	v_add_f32_dpp v68, v68, v68 quad_perm:[1,0,3,2] row_mask:0xf bank_mask:0xf bound_ctrl:1
	ds_read_b128 v[118:121], v84 offset:26368
	v_add_f32_dpp v82, v69, v69 row_ror:8 row_mask:0xf bank_mask:0xf bound_ctrl:1
	v_add_f32_dpp v68, v68, v68 quad_perm:[2,3,0,1] row_mask:0xf bank_mask:0xf bound_ctrl:1
	ds_read_b32 v126, v85 offset:41408
	ds_read_b128 v[122:125], v84 offset:9984
	v_add_f32_dpp v68, v68, v68 row_half_mirror row_mask:0xf bank_mask:0xf bound_ctrl:1
	ds_read_b128 v[110:113], v84 offset:34560
	ds_read_b128 v[114:117], v84 offset:18176
	v_add_f32_dpp v68, v68, v68 row_ror:8 row_mask:0xf bank_mask:0xf bound_ctrl:1
	v_pk_fma_f32 v[78:79], v[32:33], v[68:69], v[74:75] op_sel_hi:[1,0,1] neg_lo:[0,1,0] neg_hi:[0,1,0]
	v_pk_fma_f32 v[80:81], v[34:35], v[68:69], v[76:77] op_sel_hi:[1,0,1] neg_lo:[0,1,0] neg_hi:[0,1,0]
	s_waitcnt lgkmcnt(6)
	v_pk_mul_f32 v[68:69], v[46:47], v[78:79] op_sel_hi:[1,0]
	v_pk_mul_f32 v[70:71], v[66:67], v[58:59] op_sel_hi:[0,1]
	v_pk_fma_f32 v[68:69], v[48:49], v[78:79], v[68:69] op_sel:[0,1,0]
	v_pk_mul_f32 v[72:73], v[66:67], v[60:61] op_sel_hi:[0,1]
	v_pk_fma_f32 v[68:69], v[62:63], v[80:81], v[68:69] op_sel_hi:[1,0,1]
	v_pk_fma_f32 v[74:75], v[50:51], v[78:79], v[70:71]
	v_pk_fma_f32 v[68:69], v[64:65], v[80:81], v[68:69] op_sel:[0,1,0]
	v_pk_fma_f32 v[76:77], v[52:53], v[80:81], v[72:73]
	ds_read_b128 v[2:5], v84 offset:2048
	v_add_f32_dpp v68, v68, v68 quad_perm:[1,0,3,2] row_mask:0xf bank_mask:0xf bound_ctrl:1
	ds_read_b128 v[14:17], v84 offset:26624
	v_add_f32_dpp v88, v69, v69 row_ror:8 row_mask:0xf bank_mask:0xf bound_ctrl:1
	v_add_f32_dpp v68, v68, v68 quad_perm:[2,3,0,1] row_mask:0xf bank_mask:0xf bound_ctrl:1
	ds_write2st64_b32 v86, v82, v88 offset0:8 offset1:10
	ds_read_b32 v22, v85 offset:41472
	v_add_f32_dpp v68, v68, v68 row_half_mirror row_mask:0xf bank_mask:0xf bound_ctrl:1
	ds_read_b128 v[18:21], v84 offset:10240
	ds_read_b128 v[6:9], v84 offset:34816
	v_add_f32_dpp v68, v68, v68 row_ror:8 row_mask:0xf bank_mask:0xf bound_ctrl:1
	ds_read_b128 v[10:13], v84 offset:18432
	v_pk_fma_f32 v[78:79], v[54:55], v[68:69], v[74:75] op_sel_hi:[1,0,1] neg_lo:[0,1,0] neg_hi:[0,1,0]
	v_pk_fma_f32 v[80:81], v[56:57], v[68:69], v[76:77] op_sel_hi:[1,0,1] neg_lo:[0,1,0] neg_hi:[0,1,0]
	s_waitcnt lgkmcnt(7)
	v_pk_mul_f32 v[68:69], v[106:107], v[78:79] op_sel_hi:[1,0]
	v_pk_mul_f32 v[70:71], v[126:127], v[118:119] op_sel_hi:[0,1]
	v_pk_fma_f32 v[68:69], v[108:109], v[78:79], v[68:69] op_sel:[0,1,0]
	v_pk_mul_f32 v[72:73], v[126:127], v[120:121] op_sel_hi:[0,1]
	v_pk_fma_f32 v[68:69], v[122:123], v[80:81], v[68:69] op_sel_hi:[1,0,1]
	v_pk_fma_f32 v[74:75], v[110:111], v[78:79], v[70:71]
	v_pk_fma_f32 v[68:69], v[124:125], v[80:81], v[68:69] op_sel:[0,1,0]
	v_pk_fma_f32 v[76:77], v[112:113], v[80:81], v[72:73]
	ds_read_b128 v[24:27], v84 offset:2304
	v_add_f32_dpp v68, v68, v68 quad_perm:[1,0,3,2] row_mask:0xf bank_mask:0xf bound_ctrl:1
	ds_read_b128 v[36:39], v84 offset:26880
	v_add_f32_dpp v82, v69, v69 row_ror:8 row_mask:0xf bank_mask:0xf bound_ctrl:1
	v_add_f32_dpp v68, v68, v68 quad_perm:[2,3,0,1] row_mask:0xf bank_mask:0xf bound_ctrl:1
	ds_read_b32 v44, v85 offset:41536
	ds_read_b128 v[40:43], v84 offset:10496
	v_add_f32_dpp v68, v68, v68 row_half_mirror row_mask:0xf bank_mask:0xf bound_ctrl:1
	ds_read_b128 v[28:31], v84 offset:35072
	ds_read_b128 v[32:35], v84 offset:18688
	v_add_f32_dpp v68, v68, v68 row_ror:8 row_mask:0xf bank_mask:0xf bound_ctrl:1
	v_pk_fma_f32 v[78:79], v[114:115], v[68:69], v[74:75] op_sel_hi:[1,0,1] neg_lo:[0,1,0] neg_hi:[0,1,0]
	v_pk_fma_f32 v[80:81], v[116:117], v[68:69], v[76:77] op_sel_hi:[1,0,1] neg_lo:[0,1,0] neg_hi:[0,1,0]
	s_waitcnt lgkmcnt(6)
	v_pk_mul_f32 v[68:69], v[2:3], v[78:79] op_sel_hi:[1,0]
	v_pk_mul_f32 v[70:71], v[22:23], v[14:15] op_sel_hi:[0,1]
	v_pk_fma_f32 v[68:69], v[4:5], v[78:79], v[68:69] op_sel:[0,1,0]
	v_pk_mul_f32 v[72:73], v[22:23], v[16:17] op_sel_hi:[0,1]
	v_pk_fma_f32 v[68:69], v[18:19], v[80:81], v[68:69] op_sel_hi:[1,0,1]
	v_pk_fma_f32 v[74:75], v[6:7], v[78:79], v[70:71]
	v_pk_fma_f32 v[68:69], v[20:21], v[80:81], v[68:69] op_sel:[0,1,0]
	v_pk_fma_f32 v[76:77], v[8:9], v[80:81], v[72:73]
	ds_read_b128 v[46:49], v84 offset:2560
	v_add_f32_dpp v68, v68, v68 quad_perm:[1,0,3,2] row_mask:0xf bank_mask:0xf bound_ctrl:1
	ds_read_b128 v[58:61], v84 offset:27136
	v_add_f32_dpp v88, v69, v69 row_ror:8 row_mask:0xf bank_mask:0xf bound_ctrl:1
	v_add_f32_dpp v68, v68, v68 quad_perm:[2,3,0,1] row_mask:0xf bank_mask:0xf bound_ctrl:1
	ds_write2st64_b32 v86, v82, v88 offset0:12 offset1:14
	ds_read_b32 v66, v85 offset:41600
	v_add_f32_dpp v68, v68, v68 row_half_mirror row_mask:0xf bank_mask:0xf bound_ctrl:1
	ds_read_b128 v[62:65], v84 offset:10752
	ds_read_b128 v[50:53], v84 offset:35328
	v_add_f32_dpp v68, v68, v68 row_ror:8 row_mask:0xf bank_mask:0xf bound_ctrl:1
	ds_read_b128 v[54:57], v84 offset:18944
	v_pk_fma_f32 v[78:79], v[10:11], v[68:69], v[74:75] op_sel_hi:[1,0,1] neg_lo:[0,1,0] neg_hi:[0,1,0]
	v_pk_fma_f32 v[80:81], v[12:13], v[68:69], v[76:77] op_sel_hi:[1,0,1] neg_lo:[0,1,0] neg_hi:[0,1,0]
	s_waitcnt lgkmcnt(7)
	v_pk_mul_f32 v[68:69], v[24:25], v[78:79] op_sel_hi:[1,0]
	v_pk_mul_f32 v[70:71], v[44:45], v[36:37] op_sel_hi:[0,1]
	v_pk_fma_f32 v[68:69], v[26:27], v[78:79], v[68:69] op_sel:[0,1,0]
	v_pk_mul_f32 v[72:73], v[44:45], v[38:39] op_sel_hi:[0,1]
	v_pk_fma_f32 v[68:69], v[40:41], v[80:81], v[68:69] op_sel_hi:[1,0,1]
	v_pk_fma_f32 v[74:75], v[28:29], v[78:79], v[70:71]
	v_pk_fma_f32 v[68:69], v[42:43], v[80:81], v[68:69] op_sel:[0,1,0]
	v_pk_fma_f32 v[76:77], v[30:31], v[80:81], v[72:73]
	ds_read_b128 v[106:109], v84 offset:2816
	v_add_f32_dpp v68, v68, v68 quad_perm:[1,0,3,2] row_mask:0xf bank_mask:0xf bound_ctrl:1
	ds_read_b128 v[118:121], v84 offset:27392
	v_add_f32_dpp v82, v69, v69 row_ror:8 row_mask:0xf bank_mask:0xf bound_ctrl:1
	v_add_f32_dpp v68, v68, v68 quad_perm:[2,3,0,1] row_mask:0xf bank_mask:0xf bound_ctrl:1
	ds_read_b32 v126, v85 offset:41664
	ds_read_b128 v[122:125], v84 offset:11008
	v_add_f32_dpp v68, v68, v68 row_half_mirror row_mask:0xf bank_mask:0xf bound_ctrl:1
	ds_read_b128 v[110:113], v84 offset:35584
	ds_read_b128 v[114:117], v84 offset:19200
	v_add_f32_dpp v68, v68, v68 row_ror:8 row_mask:0xf bank_mask:0xf bound_ctrl:1
	v_pk_fma_f32 v[78:79], v[32:33], v[68:69], v[74:75] op_sel_hi:[1,0,1] neg_lo:[0,1,0] neg_hi:[0,1,0]
	v_pk_fma_f32 v[80:81], v[34:35], v[68:69], v[76:77] op_sel_hi:[1,0,1] neg_lo:[0,1,0] neg_hi:[0,1,0]
	s_waitcnt lgkmcnt(6)
	v_pk_mul_f32 v[68:69], v[46:47], v[78:79] op_sel_hi:[1,0]
	v_pk_mul_f32 v[70:71], v[66:67], v[58:59] op_sel_hi:[0,1]
	v_pk_fma_f32 v[68:69], v[48:49], v[78:79], v[68:69] op_sel:[0,1,0]
	v_pk_mul_f32 v[72:73], v[66:67], v[60:61] op_sel_hi:[0,1]
	v_pk_fma_f32 v[68:69], v[62:63], v[80:81], v[68:69] op_sel_hi:[1,0,1]
	v_pk_fma_f32 v[74:75], v[50:51], v[78:79], v[70:71]
	v_pk_fma_f32 v[68:69], v[64:65], v[80:81], v[68:69] op_sel:[0,1,0]
	v_pk_fma_f32 v[76:77], v[52:53], v[80:81], v[72:73]
	ds_read_b128 v[2:5], v84 offset:3072
	v_add_f32_dpp v68, v68, v68 quad_perm:[1,0,3,2] row_mask:0xf bank_mask:0xf bound_ctrl:1
	ds_read_b128 v[14:17], v84 offset:27648
	v_add_f32_dpp v88, v69, v69 row_ror:8 row_mask:0xf bank_mask:0xf bound_ctrl:1
	v_add_f32_dpp v68, v68, v68 quad_perm:[2,3,0,1] row_mask:0xf bank_mask:0xf bound_ctrl:1
	ds_write2st64_b32 v86, v82, v88 offset0:16 offset1:18
	ds_read_b32 v22, v85 offset:41728
	v_add_f32_dpp v68, v68, v68 row_half_mirror row_mask:0xf bank_mask:0xf bound_ctrl:1
	ds_read_b128 v[18:21], v84 offset:11264
	ds_read_b128 v[6:9], v84 offset:35840
	v_add_f32_dpp v68, v68, v68 row_ror:8 row_mask:0xf bank_mask:0xf bound_ctrl:1
	ds_read_b128 v[10:13], v84 offset:19456
	v_pk_fma_f32 v[78:79], v[54:55], v[68:69], v[74:75] op_sel_hi:[1,0,1] neg_lo:[0,1,0] neg_hi:[0,1,0]
	v_pk_fma_f32 v[80:81], v[56:57], v[68:69], v[76:77] op_sel_hi:[1,0,1] neg_lo:[0,1,0] neg_hi:[0,1,0]
	s_waitcnt lgkmcnt(7)
	v_pk_mul_f32 v[68:69], v[106:107], v[78:79] op_sel_hi:[1,0]
	v_pk_mul_f32 v[70:71], v[126:127], v[118:119] op_sel_hi:[0,1]
	v_pk_fma_f32 v[68:69], v[108:109], v[78:79], v[68:69] op_sel:[0,1,0]
	v_pk_mul_f32 v[72:73], v[126:127], v[120:121] op_sel_hi:[0,1]
	v_pk_fma_f32 v[68:69], v[122:123], v[80:81], v[68:69] op_sel_hi:[1,0,1]
	v_pk_fma_f32 v[74:75], v[110:111], v[78:79], v[70:71]
	v_pk_fma_f32 v[68:69], v[124:125], v[80:81], v[68:69] op_sel:[0,1,0]
	v_pk_fma_f32 v[76:77], v[112:113], v[80:81], v[72:73]
	ds_read_b128 v[24:27], v84 offset:3328
	v_add_f32_dpp v68, v68, v68 quad_perm:[1,0,3,2] row_mask:0xf bank_mask:0xf bound_ctrl:1
	ds_read_b128 v[36:39], v84 offset:27904
	v_add_f32_dpp v82, v69, v69 row_ror:8 row_mask:0xf bank_mask:0xf bound_ctrl:1
	v_add_f32_dpp v68, v68, v68 quad_perm:[2,3,0,1] row_mask:0xf bank_mask:0xf bound_ctrl:1
	ds_read_b32 v44, v85 offset:41792
	ds_read_b128 v[40:43], v84 offset:11520
	v_add_f32_dpp v68, v68, v68 row_half_mirror row_mask:0xf bank_mask:0xf bound_ctrl:1
	ds_read_b128 v[28:31], v84 offset:36096
	ds_read_b128 v[32:35], v84 offset:19712
	v_add_f32_dpp v68, v68, v68 row_ror:8 row_mask:0xf bank_mask:0xf bound_ctrl:1
	v_pk_fma_f32 v[78:79], v[114:115], v[68:69], v[74:75] op_sel_hi:[1,0,1] neg_lo:[0,1,0] neg_hi:[0,1,0]
	v_pk_fma_f32 v[80:81], v[116:117], v[68:69], v[76:77] op_sel_hi:[1,0,1] neg_lo:[0,1,0] neg_hi:[0,1,0]
	s_waitcnt lgkmcnt(6)
	v_pk_mul_f32 v[68:69], v[2:3], v[78:79] op_sel_hi:[1,0]
	v_pk_mul_f32 v[70:71], v[22:23], v[14:15] op_sel_hi:[0,1]
	v_pk_fma_f32 v[68:69], v[4:5], v[78:79], v[68:69] op_sel:[0,1,0]
	v_pk_mul_f32 v[72:73], v[22:23], v[16:17] op_sel_hi:[0,1]
	v_pk_fma_f32 v[68:69], v[18:19], v[80:81], v[68:69] op_sel_hi:[1,0,1]
	v_pk_fma_f32 v[74:75], v[6:7], v[78:79], v[70:71]
	v_pk_fma_f32 v[68:69], v[20:21], v[80:81], v[68:69] op_sel:[0,1,0]
	v_pk_fma_f32 v[76:77], v[8:9], v[80:81], v[72:73]
	ds_read_b128 v[46:49], v84 offset:3584
	v_add_f32_dpp v68, v68, v68 quad_perm:[1,0,3,2] row_mask:0xf bank_mask:0xf bound_ctrl:1
	ds_read_b128 v[58:61], v84 offset:28160
	v_add_f32_dpp v88, v69, v69 row_ror:8 row_mask:0xf bank_mask:0xf bound_ctrl:1
	v_add_f32_dpp v68, v68, v68 quad_perm:[2,3,0,1] row_mask:0xf bank_mask:0xf bound_ctrl:1
	ds_write2st64_b32 v86, v82, v88 offset0:20 offset1:22
	ds_read_b32 v66, v85 offset:41856
	v_add_f32_dpp v68, v68, v68 row_half_mirror row_mask:0xf bank_mask:0xf bound_ctrl:1
	ds_read_b128 v[62:65], v84 offset:11776
	ds_read_b128 v[50:53], v84 offset:36352
	v_add_f32_dpp v68, v68, v68 row_ror:8 row_mask:0xf bank_mask:0xf bound_ctrl:1
	ds_read_b128 v[54:57], v84 offset:19968
	v_pk_fma_f32 v[78:79], v[10:11], v[68:69], v[74:75] op_sel_hi:[1,0,1] neg_lo:[0,1,0] neg_hi:[0,1,0]
	v_pk_fma_f32 v[80:81], v[12:13], v[68:69], v[76:77] op_sel_hi:[1,0,1] neg_lo:[0,1,0] neg_hi:[0,1,0]
	s_waitcnt lgkmcnt(7)
	v_pk_mul_f32 v[68:69], v[24:25], v[78:79] op_sel_hi:[1,0]
	v_pk_mul_f32 v[70:71], v[44:45], v[36:37] op_sel_hi:[0,1]
	v_pk_fma_f32 v[68:69], v[26:27], v[78:79], v[68:69] op_sel:[0,1,0]
	v_pk_mul_f32 v[72:73], v[44:45], v[38:39] op_sel_hi:[0,1]
	v_pk_fma_f32 v[68:69], v[40:41], v[80:81], v[68:69] op_sel_hi:[1,0,1]
	v_pk_fma_f32 v[74:75], v[28:29], v[78:79], v[70:71]
	v_pk_fma_f32 v[68:69], v[42:43], v[80:81], v[68:69] op_sel:[0,1,0]
	v_pk_fma_f32 v[76:77], v[30:31], v[80:81], v[72:73]
	ds_read_b128 v[106:109], v84 offset:3840
	v_add_f32_dpp v68, v68, v68 quad_perm:[1,0,3,2] row_mask:0xf bank_mask:0xf bound_ctrl:1
	ds_read_b128 v[118:121], v84 offset:28416
	v_add_f32_dpp v82, v69, v69 row_ror:8 row_mask:0xf bank_mask:0xf bound_ctrl:1
	v_add_f32_dpp v68, v68, v68 quad_perm:[2,3,0,1] row_mask:0xf bank_mask:0xf bound_ctrl:1
	ds_read_b32 v126, v85 offset:41920
	ds_read_b128 v[122:125], v84 offset:12032
	v_add_f32_dpp v68, v68, v68 row_half_mirror row_mask:0xf bank_mask:0xf bound_ctrl:1
	ds_read_b128 v[110:113], v84 offset:36608
	ds_read_b128 v[114:117], v84 offset:20224
	v_add_f32_dpp v68, v68, v68 row_ror:8 row_mask:0xf bank_mask:0xf bound_ctrl:1
	v_pk_fma_f32 v[78:79], v[32:33], v[68:69], v[74:75] op_sel_hi:[1,0,1] neg_lo:[0,1,0] neg_hi:[0,1,0]
	v_pk_fma_f32 v[80:81], v[34:35], v[68:69], v[76:77] op_sel_hi:[1,0,1] neg_lo:[0,1,0] neg_hi:[0,1,0]
	s_waitcnt lgkmcnt(6)
	v_pk_mul_f32 v[68:69], v[46:47], v[78:79] op_sel_hi:[1,0]
	v_pk_mul_f32 v[70:71], v[66:67], v[58:59] op_sel_hi:[0,1]
	v_pk_fma_f32 v[68:69], v[48:49], v[78:79], v[68:69] op_sel:[0,1,0]
	v_pk_mul_f32 v[72:73], v[66:67], v[60:61] op_sel_hi:[0,1]
	v_pk_fma_f32 v[68:69], v[62:63], v[80:81], v[68:69] op_sel_hi:[1,0,1]
	v_pk_fma_f32 v[74:75], v[50:51], v[78:79], v[70:71]
	v_pk_fma_f32 v[68:69], v[64:65], v[80:81], v[68:69] op_sel:[0,1,0]
	v_pk_fma_f32 v[76:77], v[52:53], v[80:81], v[72:73]
	ds_read_b128 v[2:5], v84 offset:4096
	v_add_f32_dpp v68, v68, v68 quad_perm:[1,0,3,2] row_mask:0xf bank_mask:0xf bound_ctrl:1
	ds_read_b128 v[14:17], v84 offset:28672
	v_add_f32_dpp v88, v69, v69 row_ror:8 row_mask:0xf bank_mask:0xf bound_ctrl:1
	v_add_f32_dpp v68, v68, v68 quad_perm:[2,3,0,1] row_mask:0xf bank_mask:0xf bound_ctrl:1
	ds_write2st64_b32 v86, v82, v88 offset0:24 offset1:26
	ds_read_b32 v22, v85 offset:41984
	v_add_f32_dpp v68, v68, v68 row_half_mirror row_mask:0xf bank_mask:0xf bound_ctrl:1
	ds_read_b128 v[18:21], v84 offset:12288
	ds_read_b128 v[6:9], v84 offset:36864
	v_add_f32_dpp v68, v68, v68 row_ror:8 row_mask:0xf bank_mask:0xf bound_ctrl:1
	ds_read_b128 v[10:13], v84 offset:20480
	v_pk_fma_f32 v[78:79], v[54:55], v[68:69], v[74:75] op_sel_hi:[1,0,1] neg_lo:[0,1,0] neg_hi:[0,1,0]
	v_pk_fma_f32 v[80:81], v[56:57], v[68:69], v[76:77] op_sel_hi:[1,0,1] neg_lo:[0,1,0] neg_hi:[0,1,0]
	s_waitcnt lgkmcnt(7)
	v_pk_mul_f32 v[68:69], v[106:107], v[78:79] op_sel_hi:[1,0]
	v_pk_mul_f32 v[70:71], v[126:127], v[118:119] op_sel_hi:[0,1]
	v_pk_fma_f32 v[68:69], v[108:109], v[78:79], v[68:69] op_sel:[0,1,0]
	v_pk_mul_f32 v[72:73], v[126:127], v[120:121] op_sel_hi:[0,1]
	v_pk_fma_f32 v[68:69], v[122:123], v[80:81], v[68:69] op_sel_hi:[1,0,1]
	v_pk_fma_f32 v[74:75], v[110:111], v[78:79], v[70:71]
	v_pk_fma_f32 v[68:69], v[124:125], v[80:81], v[68:69] op_sel:[0,1,0]
	v_pk_fma_f32 v[76:77], v[112:113], v[80:81], v[72:73]
	ds_read_b128 v[24:27], v84 offset:4352
	v_add_f32_dpp v68, v68, v68 quad_perm:[1,0,3,2] row_mask:0xf bank_mask:0xf bound_ctrl:1
	ds_read_b128 v[36:39], v84 offset:28928
	v_add_f32_dpp v82, v69, v69 row_ror:8 row_mask:0xf bank_mask:0xf bound_ctrl:1
	v_add_f32_dpp v68, v68, v68 quad_perm:[2,3,0,1] row_mask:0xf bank_mask:0xf bound_ctrl:1
	ds_read_b32 v44, v85 offset:42048
	ds_read_b128 v[40:43], v84 offset:12544
	v_add_f32_dpp v68, v68, v68 row_half_mirror row_mask:0xf bank_mask:0xf bound_ctrl:1
	ds_read_b128 v[28:31], v84 offset:37120
	ds_read_b128 v[32:35], v84 offset:20736
	v_add_f32_dpp v68, v68, v68 row_ror:8 row_mask:0xf bank_mask:0xf bound_ctrl:1
	v_pk_fma_f32 v[78:79], v[114:115], v[68:69], v[74:75] op_sel_hi:[1,0,1] neg_lo:[0,1,0] neg_hi:[0,1,0]
	v_pk_fma_f32 v[80:81], v[116:117], v[68:69], v[76:77] op_sel_hi:[1,0,1] neg_lo:[0,1,0] neg_hi:[0,1,0]
	s_waitcnt lgkmcnt(6)
	v_pk_mul_f32 v[68:69], v[2:3], v[78:79] op_sel_hi:[1,0]
	v_pk_mul_f32 v[70:71], v[22:23], v[14:15] op_sel_hi:[0,1]
	v_pk_fma_f32 v[68:69], v[4:5], v[78:79], v[68:69] op_sel:[0,1,0]
	v_pk_mul_f32 v[72:73], v[22:23], v[16:17] op_sel_hi:[0,1]
	v_pk_fma_f32 v[68:69], v[18:19], v[80:81], v[68:69] op_sel_hi:[1,0,1]
	v_pk_fma_f32 v[74:75], v[6:7], v[78:79], v[70:71]
	v_pk_fma_f32 v[68:69], v[20:21], v[80:81], v[68:69] op_sel:[0,1,0]
	v_pk_fma_f32 v[76:77], v[8:9], v[80:81], v[72:73]
	ds_read_b128 v[46:49], v84 offset:4608
	v_add_f32_dpp v68, v68, v68 quad_perm:[1,0,3,2] row_mask:0xf bank_mask:0xf bound_ctrl:1
	ds_read_b128 v[58:61], v84 offset:29184
	v_add_f32_dpp v88, v69, v69 row_ror:8 row_mask:0xf bank_mask:0xf bound_ctrl:1
	v_add_f32_dpp v68, v68, v68 quad_perm:[2,3,0,1] row_mask:0xf bank_mask:0xf bound_ctrl:1
	ds_write2st64_b32 v86, v82, v88 offset0:28 offset1:30
	ds_read_b32 v66, v85 offset:42112
	v_add_f32_dpp v68, v68, v68 row_half_mirror row_mask:0xf bank_mask:0xf bound_ctrl:1
	ds_read_b128 v[62:65], v84 offset:12800
	ds_read_b128 v[50:53], v84 offset:37376
	v_add_f32_dpp v68, v68, v68 row_ror:8 row_mask:0xf bank_mask:0xf bound_ctrl:1
	ds_read_b128 v[54:57], v84 offset:20992
	v_pk_fma_f32 v[78:79], v[10:11], v[68:69], v[74:75] op_sel_hi:[1,0,1] neg_lo:[0,1,0] neg_hi:[0,1,0]
	v_pk_fma_f32 v[80:81], v[12:13], v[68:69], v[76:77] op_sel_hi:[1,0,1] neg_lo:[0,1,0] neg_hi:[0,1,0]
	s_waitcnt lgkmcnt(7)
	v_pk_mul_f32 v[68:69], v[24:25], v[78:79] op_sel_hi:[1,0]
	v_pk_mul_f32 v[70:71], v[44:45], v[36:37] op_sel_hi:[0,1]
	v_pk_fma_f32 v[68:69], v[26:27], v[78:79], v[68:69] op_sel:[0,1,0]
	v_pk_mul_f32 v[72:73], v[44:45], v[38:39] op_sel_hi:[0,1]
	v_pk_fma_f32 v[68:69], v[40:41], v[80:81], v[68:69] op_sel_hi:[1,0,1]
	v_pk_fma_f32 v[74:75], v[28:29], v[78:79], v[70:71]
	v_pk_fma_f32 v[68:69], v[42:43], v[80:81], v[68:69] op_sel:[0,1,0]
	v_pk_fma_f32 v[76:77], v[30:31], v[80:81], v[72:73]
	ds_read_b128 v[106:109], v84 offset:4864
	v_add_f32_dpp v68, v68, v68 quad_perm:[1,0,3,2] row_mask:0xf bank_mask:0xf bound_ctrl:1
	ds_read_b128 v[118:121], v84 offset:29440
	v_add_f32_dpp v82, v69, v69 row_ror:8 row_mask:0xf bank_mask:0xf bound_ctrl:1
	v_add_f32_dpp v68, v68, v68 quad_perm:[2,3,0,1] row_mask:0xf bank_mask:0xf bound_ctrl:1
	ds_read_b32 v126, v85 offset:42176
	ds_read_b128 v[122:125], v84 offset:13056
	v_add_f32_dpp v68, v68, v68 row_half_mirror row_mask:0xf bank_mask:0xf bound_ctrl:1
	ds_read_b128 v[110:113], v84 offset:37632
	ds_read_b128 v[114:117], v84 offset:21248
	v_add_f32_dpp v68, v68, v68 row_ror:8 row_mask:0xf bank_mask:0xf bound_ctrl:1
	v_pk_fma_f32 v[78:79], v[32:33], v[68:69], v[74:75] op_sel_hi:[1,0,1] neg_lo:[0,1,0] neg_hi:[0,1,0]
	v_pk_fma_f32 v[80:81], v[34:35], v[68:69], v[76:77] op_sel_hi:[1,0,1] neg_lo:[0,1,0] neg_hi:[0,1,0]
	s_waitcnt lgkmcnt(6)
	v_pk_mul_f32 v[68:69], v[46:47], v[78:79] op_sel_hi:[1,0]
	v_pk_mul_f32 v[70:71], v[66:67], v[58:59] op_sel_hi:[0,1]
	v_pk_fma_f32 v[68:69], v[48:49], v[78:79], v[68:69] op_sel:[0,1,0]
	v_pk_mul_f32 v[72:73], v[66:67], v[60:61] op_sel_hi:[0,1]
	v_pk_fma_f32 v[68:69], v[62:63], v[80:81], v[68:69] op_sel_hi:[1,0,1]
	v_pk_fma_f32 v[74:75], v[50:51], v[78:79], v[70:71]
	v_pk_fma_f32 v[68:69], v[64:65], v[80:81], v[68:69] op_sel:[0,1,0]
	v_pk_fma_f32 v[76:77], v[52:53], v[80:81], v[72:73]
	ds_read_b128 v[2:5], v84 offset:5120
	v_add_f32_dpp v68, v68, v68 quad_perm:[1,0,3,2] row_mask:0xf bank_mask:0xf bound_ctrl:1
	ds_read_b128 v[14:17], v84 offset:29696
	v_add_f32_dpp v88, v69, v69 row_ror:8 row_mask:0xf bank_mask:0xf bound_ctrl:1
	v_add_f32_dpp v68, v68, v68 quad_perm:[2,3,0,1] row_mask:0xf bank_mask:0xf bound_ctrl:1
	ds_write2st64_b32 v86, v82, v88 offset0:32 offset1:34
	ds_read_b32 v22, v85 offset:42240
	v_add_f32_dpp v68, v68, v68 row_half_mirror row_mask:0xf bank_mask:0xf bound_ctrl:1
	ds_read_b128 v[18:21], v84 offset:13312
	ds_read_b128 v[6:9], v84 offset:37888
	v_add_f32_dpp v68, v68, v68 row_ror:8 row_mask:0xf bank_mask:0xf bound_ctrl:1
	ds_read_b128 v[10:13], v84 offset:21504
	v_pk_fma_f32 v[78:79], v[54:55], v[68:69], v[74:75] op_sel_hi:[1,0,1] neg_lo:[0,1,0] neg_hi:[0,1,0]
	v_pk_fma_f32 v[80:81], v[56:57], v[68:69], v[76:77] op_sel_hi:[1,0,1] neg_lo:[0,1,0] neg_hi:[0,1,0]
	s_waitcnt lgkmcnt(7)
	v_pk_mul_f32 v[68:69], v[106:107], v[78:79] op_sel_hi:[1,0]
	v_pk_mul_f32 v[70:71], v[126:127], v[118:119] op_sel_hi:[0,1]
	v_pk_fma_f32 v[68:69], v[108:109], v[78:79], v[68:69] op_sel:[0,1,0]
	v_pk_mul_f32 v[72:73], v[126:127], v[120:121] op_sel_hi:[0,1]
	v_pk_fma_f32 v[68:69], v[122:123], v[80:81], v[68:69] op_sel_hi:[1,0,1]
	v_pk_fma_f32 v[74:75], v[110:111], v[78:79], v[70:71]
	v_pk_fma_f32 v[68:69], v[124:125], v[80:81], v[68:69] op_sel:[0,1,0]
	v_pk_fma_f32 v[76:77], v[112:113], v[80:81], v[72:73]
	ds_read_b128 v[24:27], v84 offset:5376
	v_add_f32_dpp v68, v68, v68 quad_perm:[1,0,3,2] row_mask:0xf bank_mask:0xf bound_ctrl:1
	ds_read_b128 v[36:39], v84 offset:29952
	v_add_f32_dpp v82, v69, v69 row_ror:8 row_mask:0xf bank_mask:0xf bound_ctrl:1
	v_add_f32_dpp v68, v68, v68 quad_perm:[2,3,0,1] row_mask:0xf bank_mask:0xf bound_ctrl:1
	ds_read_b32 v44, v85 offset:42304
	ds_read_b128 v[40:43], v84 offset:13568
	v_add_f32_dpp v68, v68, v68 row_half_mirror row_mask:0xf bank_mask:0xf bound_ctrl:1
	ds_read_b128 v[28:31], v84 offset:38144
	ds_read_b128 v[32:35], v84 offset:21760
	v_add_f32_dpp v68, v68, v68 row_ror:8 row_mask:0xf bank_mask:0xf bound_ctrl:1
	v_pk_fma_f32 v[78:79], v[114:115], v[68:69], v[74:75] op_sel_hi:[1,0,1] neg_lo:[0,1,0] neg_hi:[0,1,0]
	v_pk_fma_f32 v[80:81], v[116:117], v[68:69], v[76:77] op_sel_hi:[1,0,1] neg_lo:[0,1,0] neg_hi:[0,1,0]
	s_waitcnt lgkmcnt(6)
	v_pk_mul_f32 v[68:69], v[2:3], v[78:79] op_sel_hi:[1,0]
	v_pk_mul_f32 v[70:71], v[22:23], v[14:15] op_sel_hi:[0,1]
	v_pk_fma_f32 v[68:69], v[4:5], v[78:79], v[68:69] op_sel:[0,1,0]
	v_pk_mul_f32 v[72:73], v[22:23], v[16:17] op_sel_hi:[0,1]
	v_pk_fma_f32 v[68:69], v[18:19], v[80:81], v[68:69] op_sel_hi:[1,0,1]
	v_pk_fma_f32 v[74:75], v[6:7], v[78:79], v[70:71]
	v_pk_fma_f32 v[68:69], v[20:21], v[80:81], v[68:69] op_sel:[0,1,0]
	v_pk_fma_f32 v[76:77], v[8:9], v[80:81], v[72:73]
	ds_read_b128 v[46:49], v84 offset:5632
	v_add_f32_dpp v68, v68, v68 quad_perm:[1,0,3,2] row_mask:0xf bank_mask:0xf bound_ctrl:1
	ds_read_b128 v[58:61], v84 offset:30208
	v_add_f32_dpp v88, v69, v69 row_ror:8 row_mask:0xf bank_mask:0xf bound_ctrl:1
	v_add_f32_dpp v68, v68, v68 quad_perm:[2,3,0,1] row_mask:0xf bank_mask:0xf bound_ctrl:1
	ds_write2st64_b32 v86, v82, v88 offset0:36 offset1:38
	ds_read_b32 v66, v85 offset:42368
	v_add_f32_dpp v68, v68, v68 row_half_mirror row_mask:0xf bank_mask:0xf bound_ctrl:1
	ds_read_b128 v[62:65], v84 offset:13824
	ds_read_b128 v[50:53], v84 offset:38400
	v_add_f32_dpp v68, v68, v68 row_ror:8 row_mask:0xf bank_mask:0xf bound_ctrl:1
	ds_read_b128 v[54:57], v84 offset:22016
	v_pk_fma_f32 v[78:79], v[10:11], v[68:69], v[74:75] op_sel_hi:[1,0,1] neg_lo:[0,1,0] neg_hi:[0,1,0]
	v_pk_fma_f32 v[80:81], v[12:13], v[68:69], v[76:77] op_sel_hi:[1,0,1] neg_lo:[0,1,0] neg_hi:[0,1,0]
	s_waitcnt lgkmcnt(7)
	v_pk_mul_f32 v[68:69], v[24:25], v[78:79] op_sel_hi:[1,0]
	v_pk_mul_f32 v[70:71], v[44:45], v[36:37] op_sel_hi:[0,1]
	v_pk_fma_f32 v[68:69], v[26:27], v[78:79], v[68:69] op_sel:[0,1,0]
	v_pk_mul_f32 v[72:73], v[44:45], v[38:39] op_sel_hi:[0,1]
	v_pk_fma_f32 v[68:69], v[40:41], v[80:81], v[68:69] op_sel_hi:[1,0,1]
	v_pk_fma_f32 v[74:75], v[28:29], v[78:79], v[70:71]
	v_pk_fma_f32 v[68:69], v[42:43], v[80:81], v[68:69] op_sel:[0,1,0]
	v_pk_fma_f32 v[76:77], v[30:31], v[80:81], v[72:73]
	ds_read_b128 v[106:109], v84 offset:5888
	v_add_f32_dpp v68, v68, v68 quad_perm:[1,0,3,2] row_mask:0xf bank_mask:0xf bound_ctrl:1
	ds_read_b128 v[118:121], v84 offset:30464
	v_add_f32_dpp v82, v69, v69 row_ror:8 row_mask:0xf bank_mask:0xf bound_ctrl:1
	v_add_f32_dpp v68, v68, v68 quad_perm:[2,3,0,1] row_mask:0xf bank_mask:0xf bound_ctrl:1
	ds_read_b32 v126, v85 offset:42432
	ds_read_b128 v[122:125], v84 offset:14080
	v_add_f32_dpp v68, v68, v68 row_half_mirror row_mask:0xf bank_mask:0xf bound_ctrl:1
	ds_read_b128 v[110:113], v84 offset:38656
	ds_read_b128 v[114:117], v84 offset:22272
	v_add_f32_dpp v68, v68, v68 row_ror:8 row_mask:0xf bank_mask:0xf bound_ctrl:1
	v_pk_fma_f32 v[78:79], v[32:33], v[68:69], v[74:75] op_sel_hi:[1,0,1] neg_lo:[0,1,0] neg_hi:[0,1,0]
	v_pk_fma_f32 v[80:81], v[34:35], v[68:69], v[76:77] op_sel_hi:[1,0,1] neg_lo:[0,1,0] neg_hi:[0,1,0]
	s_waitcnt lgkmcnt(6)
	v_pk_mul_f32 v[68:69], v[46:47], v[78:79] op_sel_hi:[1,0]
	v_pk_mul_f32 v[70:71], v[66:67], v[58:59] op_sel_hi:[0,1]
	v_pk_fma_f32 v[68:69], v[48:49], v[78:79], v[68:69] op_sel:[0,1,0]
	v_pk_mul_f32 v[72:73], v[66:67], v[60:61] op_sel_hi:[0,1]
	v_pk_fma_f32 v[68:69], v[62:63], v[80:81], v[68:69] op_sel_hi:[1,0,1]
	v_pk_fma_f32 v[74:75], v[50:51], v[78:79], v[70:71]
	v_pk_fma_f32 v[68:69], v[64:65], v[80:81], v[68:69] op_sel:[0,1,0]
	v_pk_fma_f32 v[76:77], v[52:53], v[80:81], v[72:73]
	ds_read_b128 v[2:5], v84 offset:6144
	v_add_f32_dpp v68, v68, v68 quad_perm:[1,0,3,2] row_mask:0xf bank_mask:0xf bound_ctrl:1
	ds_read_b128 v[14:17], v84 offset:30720
	v_add_f32_dpp v88, v69, v69 row_ror:8 row_mask:0xf bank_mask:0xf bound_ctrl:1
	v_add_f32_dpp v68, v68, v68 quad_perm:[2,3,0,1] row_mask:0xf bank_mask:0xf bound_ctrl:1
	ds_write2st64_b32 v86, v82, v88 offset0:40 offset1:42
	ds_read_b32 v22, v85 offset:42496
	v_add_f32_dpp v68, v68, v68 row_half_mirror row_mask:0xf bank_mask:0xf bound_ctrl:1
	ds_read_b128 v[18:21], v84 offset:14336
	ds_read_b128 v[6:9], v84 offset:38912
	v_add_f32_dpp v68, v68, v68 row_ror:8 row_mask:0xf bank_mask:0xf bound_ctrl:1
	ds_read_b128 v[10:13], v84 offset:22528
	v_pk_fma_f32 v[78:79], v[54:55], v[68:69], v[74:75] op_sel_hi:[1,0,1] neg_lo:[0,1,0] neg_hi:[0,1,0]
	v_pk_fma_f32 v[80:81], v[56:57], v[68:69], v[76:77] op_sel_hi:[1,0,1] neg_lo:[0,1,0] neg_hi:[0,1,0]
	s_waitcnt lgkmcnt(7)
	v_pk_mul_f32 v[68:69], v[106:107], v[78:79] op_sel_hi:[1,0]
	v_pk_mul_f32 v[70:71], v[126:127], v[118:119] op_sel_hi:[0,1]
	v_pk_fma_f32 v[68:69], v[108:109], v[78:79], v[68:69] op_sel:[0,1,0]
	v_pk_mul_f32 v[72:73], v[126:127], v[120:121] op_sel_hi:[0,1]
	v_pk_fma_f32 v[68:69], v[122:123], v[80:81], v[68:69] op_sel_hi:[1,0,1]
	v_pk_fma_f32 v[74:75], v[110:111], v[78:79], v[70:71]
	v_pk_fma_f32 v[68:69], v[124:125], v[80:81], v[68:69] op_sel:[0,1,0]
	v_pk_fma_f32 v[76:77], v[112:113], v[80:81], v[72:73]
	ds_read_b128 v[24:27], v84 offset:6400
	v_add_f32_dpp v68, v68, v68 quad_perm:[1,0,3,2] row_mask:0xf bank_mask:0xf bound_ctrl:1
	ds_read_b128 v[36:39], v84 offset:30976
	v_add_f32_dpp v82, v69, v69 row_ror:8 row_mask:0xf bank_mask:0xf bound_ctrl:1
	v_add_f32_dpp v68, v68, v68 quad_perm:[2,3,0,1] row_mask:0xf bank_mask:0xf bound_ctrl:1
	ds_read_b32 v44, v85 offset:42560
	ds_read_b128 v[40:43], v84 offset:14592
	v_add_f32_dpp v68, v68, v68 row_half_mirror row_mask:0xf bank_mask:0xf bound_ctrl:1
	ds_read_b128 v[28:31], v84 offset:39168
	ds_read_b128 v[32:35], v84 offset:22784
	v_add_f32_dpp v68, v68, v68 row_ror:8 row_mask:0xf bank_mask:0xf bound_ctrl:1
	v_pk_fma_f32 v[78:79], v[114:115], v[68:69], v[74:75] op_sel_hi:[1,0,1] neg_lo:[0,1,0] neg_hi:[0,1,0]
	v_pk_fma_f32 v[80:81], v[116:117], v[68:69], v[76:77] op_sel_hi:[1,0,1] neg_lo:[0,1,0] neg_hi:[0,1,0]
	s_waitcnt lgkmcnt(6)
	v_pk_mul_f32 v[68:69], v[2:3], v[78:79] op_sel_hi:[1,0]
	v_pk_mul_f32 v[70:71], v[22:23], v[14:15] op_sel_hi:[0,1]
	v_pk_fma_f32 v[68:69], v[4:5], v[78:79], v[68:69] op_sel:[0,1,0]
	v_pk_mul_f32 v[72:73], v[22:23], v[16:17] op_sel_hi:[0,1]
	v_pk_fma_f32 v[68:69], v[18:19], v[80:81], v[68:69] op_sel_hi:[1,0,1]
	v_pk_fma_f32 v[74:75], v[6:7], v[78:79], v[70:71]
	v_pk_fma_f32 v[68:69], v[20:21], v[80:81], v[68:69] op_sel:[0,1,0]
	v_pk_fma_f32 v[76:77], v[8:9], v[80:81], v[72:73]
	ds_read_b128 v[46:49], v84 offset:6656
	v_add_f32_dpp v68, v68, v68 quad_perm:[1,0,3,2] row_mask:0xf bank_mask:0xf bound_ctrl:1
	ds_read_b128 v[58:61], v84 offset:31232
	v_add_f32_dpp v88, v69, v69 row_ror:8 row_mask:0xf bank_mask:0xf bound_ctrl:1
	v_add_f32_dpp v68, v68, v68 quad_perm:[2,3,0,1] row_mask:0xf bank_mask:0xf bound_ctrl:1
	ds_write2st64_b32 v86, v82, v88 offset0:44 offset1:46
	ds_read_b32 v66, v85 offset:42624
	v_add_f32_dpp v68, v68, v68 row_half_mirror row_mask:0xf bank_mask:0xf bound_ctrl:1
	ds_read_b128 v[62:65], v84 offset:14848
	ds_read_b128 v[50:53], v84 offset:39424
	v_add_f32_dpp v68, v68, v68 row_ror:8 row_mask:0xf bank_mask:0xf bound_ctrl:1
	ds_read_b128 v[54:57], v84 offset:23040
	v_pk_fma_f32 v[78:79], v[10:11], v[68:69], v[74:75] op_sel_hi:[1,0,1] neg_lo:[0,1,0] neg_hi:[0,1,0]
	v_pk_fma_f32 v[80:81], v[12:13], v[68:69], v[76:77] op_sel_hi:[1,0,1] neg_lo:[0,1,0] neg_hi:[0,1,0]
	s_waitcnt lgkmcnt(7)
	v_pk_mul_f32 v[68:69], v[24:25], v[78:79] op_sel_hi:[1,0]
	v_pk_mul_f32 v[70:71], v[44:45], v[36:37] op_sel_hi:[0,1]
	v_pk_fma_f32 v[68:69], v[26:27], v[78:79], v[68:69] op_sel:[0,1,0]
	v_pk_mul_f32 v[72:73], v[44:45], v[38:39] op_sel_hi:[0,1]
	v_pk_fma_f32 v[68:69], v[40:41], v[80:81], v[68:69] op_sel_hi:[1,0,1]
	v_pk_fma_f32 v[74:75], v[28:29], v[78:79], v[70:71]
	v_pk_fma_f32 v[68:69], v[42:43], v[80:81], v[68:69] op_sel:[0,1,0]
	v_pk_fma_f32 v[76:77], v[30:31], v[80:81], v[72:73]
	ds_read_b128 v[106:109], v84 offset:6912
	v_add_f32_dpp v68, v68, v68 quad_perm:[1,0,3,2] row_mask:0xf bank_mask:0xf bound_ctrl:1
	ds_read_b128 v[118:121], v84 offset:31488
	v_add_f32_dpp v82, v69, v69 row_ror:8 row_mask:0xf bank_mask:0xf bound_ctrl:1
	v_add_f32_dpp v68, v68, v68 quad_perm:[2,3,0,1] row_mask:0xf bank_mask:0xf bound_ctrl:1
	ds_read_b32 v126, v85 offset:42688
	ds_read_b128 v[122:125], v84 offset:15104
	v_add_f32_dpp v68, v68, v68 row_half_mirror row_mask:0xf bank_mask:0xf bound_ctrl:1
	ds_read_b128 v[110:113], v84 offset:39680
	ds_read_b128 v[114:117], v84 offset:23296
	v_add_f32_dpp v68, v68, v68 row_ror:8 row_mask:0xf bank_mask:0xf bound_ctrl:1
	v_pk_fma_f32 v[78:79], v[32:33], v[68:69], v[74:75] op_sel_hi:[1,0,1] neg_lo:[0,1,0] neg_hi:[0,1,0]
	v_pk_fma_f32 v[80:81], v[34:35], v[68:69], v[76:77] op_sel_hi:[1,0,1] neg_lo:[0,1,0] neg_hi:[0,1,0]
	s_waitcnt lgkmcnt(6)
	v_pk_mul_f32 v[68:69], v[46:47], v[78:79] op_sel_hi:[1,0]
	v_pk_mul_f32 v[70:71], v[66:67], v[58:59] op_sel_hi:[0,1]
	v_pk_fma_f32 v[68:69], v[48:49], v[78:79], v[68:69] op_sel:[0,1,0]
	v_pk_mul_f32 v[72:73], v[66:67], v[60:61] op_sel_hi:[0,1]
	v_pk_fma_f32 v[68:69], v[62:63], v[80:81], v[68:69] op_sel_hi:[1,0,1]
	v_pk_fma_f32 v[74:75], v[50:51], v[78:79], v[70:71]
	v_pk_fma_f32 v[68:69], v[64:65], v[80:81], v[68:69] op_sel:[0,1,0]
	v_pk_fma_f32 v[76:77], v[52:53], v[80:81], v[72:73]
	ds_read_b128 v[2:5], v84 offset:7168
	v_add_f32_dpp v68, v68, v68 quad_perm:[1,0,3,2] row_mask:0xf bank_mask:0xf bound_ctrl:1
	ds_read_b128 v[14:17], v84 offset:31744
	v_add_f32_dpp v88, v69, v69 row_ror:8 row_mask:0xf bank_mask:0xf bound_ctrl:1
	v_add_f32_dpp v68, v68, v68 quad_perm:[2,3,0,1] row_mask:0xf bank_mask:0xf bound_ctrl:1
	ds_write2st64_b32 v86, v82, v88 offset0:48 offset1:50
	ds_read_b32 v22, v85 offset:42752
	v_add_f32_dpp v68, v68, v68 row_half_mirror row_mask:0xf bank_mask:0xf bound_ctrl:1
	ds_read_b128 v[18:21], v84 offset:15360
	ds_read_b128 v[6:9], v84 offset:39936
	v_add_f32_dpp v68, v68, v68 row_ror:8 row_mask:0xf bank_mask:0xf bound_ctrl:1
	ds_read_b128 v[10:13], v84 offset:23552
	v_pk_fma_f32 v[78:79], v[54:55], v[68:69], v[74:75] op_sel_hi:[1,0,1] neg_lo:[0,1,0] neg_hi:[0,1,0]
	v_pk_fma_f32 v[80:81], v[56:57], v[68:69], v[76:77] op_sel_hi:[1,0,1] neg_lo:[0,1,0] neg_hi:[0,1,0]
	s_waitcnt lgkmcnt(7)
	v_pk_mul_f32 v[68:69], v[106:107], v[78:79] op_sel_hi:[1,0]
	v_pk_mul_f32 v[70:71], v[126:127], v[118:119] op_sel_hi:[0,1]
	v_pk_fma_f32 v[68:69], v[108:109], v[78:79], v[68:69] op_sel:[0,1,0]
	v_pk_mul_f32 v[72:73], v[126:127], v[120:121] op_sel_hi:[0,1]
	v_pk_fma_f32 v[68:69], v[122:123], v[80:81], v[68:69] op_sel_hi:[1,0,1]
	v_pk_fma_f32 v[74:75], v[110:111], v[78:79], v[70:71]
	v_pk_fma_f32 v[68:69], v[124:125], v[80:81], v[68:69] op_sel:[0,1,0]
	v_pk_fma_f32 v[76:77], v[112:113], v[80:81], v[72:73]
	ds_read_b128 v[24:27], v84 offset:7424
	v_add_f32_dpp v68, v68, v68 quad_perm:[1,0,3,2] row_mask:0xf bank_mask:0xf bound_ctrl:1
	ds_read_b128 v[36:39], v84 offset:32000
	v_add_f32_dpp v82, v69, v69 row_ror:8 row_mask:0xf bank_mask:0xf bound_ctrl:1
	v_add_f32_dpp v68, v68, v68 quad_perm:[2,3,0,1] row_mask:0xf bank_mask:0xf bound_ctrl:1
	ds_read_b32 v44, v85 offset:42816
	ds_read_b128 v[40:43], v84 offset:15616
	v_add_f32_dpp v68, v68, v68 row_half_mirror row_mask:0xf bank_mask:0xf bound_ctrl:1
	ds_read_b128 v[28:31], v84 offset:40192
	ds_read_b128 v[32:35], v84 offset:23808
	v_add_f32_dpp v68, v68, v68 row_ror:8 row_mask:0xf bank_mask:0xf bound_ctrl:1
	v_pk_fma_f32 v[78:79], v[114:115], v[68:69], v[74:75] op_sel_hi:[1,0,1] neg_lo:[0,1,0] neg_hi:[0,1,0]
	v_pk_fma_f32 v[80:81], v[116:117], v[68:69], v[76:77] op_sel_hi:[1,0,1] neg_lo:[0,1,0] neg_hi:[0,1,0]
	s_waitcnt lgkmcnt(6)
	v_pk_mul_f32 v[68:69], v[2:3], v[78:79] op_sel_hi:[1,0]
	v_pk_mul_f32 v[70:71], v[22:23], v[14:15] op_sel_hi:[0,1]
	v_pk_fma_f32 v[68:69], v[4:5], v[78:79], v[68:69] op_sel:[0,1,0]
	v_pk_mul_f32 v[72:73], v[22:23], v[16:17] op_sel_hi:[0,1]
	v_pk_fma_f32 v[68:69], v[18:19], v[80:81], v[68:69] op_sel_hi:[1,0,1]
	v_pk_fma_f32 v[74:75], v[6:7], v[78:79], v[70:71]
	v_pk_fma_f32 v[68:69], v[20:21], v[80:81], v[68:69] op_sel:[0,1,0]
	v_pk_fma_f32 v[76:77], v[8:9], v[80:81], v[72:73]
	ds_read_b128 v[46:49], v84 offset:7680
	v_add_f32_dpp v68, v68, v68 quad_perm:[1,0,3,2] row_mask:0xf bank_mask:0xf bound_ctrl:1
	ds_read_b128 v[58:61], v84 offset:32256
	v_add_f32_dpp v88, v69, v69 row_ror:8 row_mask:0xf bank_mask:0xf bound_ctrl:1
	v_add_f32_dpp v68, v68, v68 quad_perm:[2,3,0,1] row_mask:0xf bank_mask:0xf bound_ctrl:1
	ds_write2st64_b32 v86, v82, v88 offset0:52 offset1:54
	ds_read_b32 v66, v85 offset:42880
	v_add_f32_dpp v68, v68, v68 row_half_mirror row_mask:0xf bank_mask:0xf bound_ctrl:1
	ds_read_b128 v[62:65], v84 offset:15872
	ds_read_b128 v[50:53], v84 offset:40448
	v_add_f32_dpp v68, v68, v68 row_ror:8 row_mask:0xf bank_mask:0xf bound_ctrl:1
	ds_read_b128 v[54:57], v84 offset:24064
	v_pk_fma_f32 v[78:79], v[10:11], v[68:69], v[74:75] op_sel_hi:[1,0,1] neg_lo:[0,1,0] neg_hi:[0,1,0]
	v_pk_fma_f32 v[80:81], v[12:13], v[68:69], v[76:77] op_sel_hi:[1,0,1] neg_lo:[0,1,0] neg_hi:[0,1,0]
	s_waitcnt lgkmcnt(7)
	v_pk_mul_f32 v[68:69], v[24:25], v[78:79] op_sel_hi:[1,0]
	v_pk_mul_f32 v[70:71], v[44:45], v[36:37] op_sel_hi:[0,1]
	v_pk_fma_f32 v[68:69], v[26:27], v[78:79], v[68:69] op_sel:[0,1,0]
	v_pk_mul_f32 v[72:73], v[44:45], v[38:39] op_sel_hi:[0,1]
	v_pk_fma_f32 v[68:69], v[40:41], v[80:81], v[68:69] op_sel_hi:[1,0,1]
	v_pk_fma_f32 v[74:75], v[28:29], v[78:79], v[70:71]
	v_pk_fma_f32 v[68:69], v[42:43], v[80:81], v[68:69] op_sel:[0,1,0]
	v_pk_fma_f32 v[76:77], v[30:31], v[80:81], v[72:73]
	ds_read_b128 v[106:109], v84 offset:7936
	v_add_f32_dpp v68, v68, v68 quad_perm:[1,0,3,2] row_mask:0xf bank_mask:0xf bound_ctrl:1
	ds_read_b128 v[118:121], v84 offset:32512
	v_add_f32_dpp v82, v69, v69 row_ror:8 row_mask:0xf bank_mask:0xf bound_ctrl:1
	v_add_f32_dpp v68, v68, v68 quad_perm:[2,3,0,1] row_mask:0xf bank_mask:0xf bound_ctrl:1
	ds_read_b32 v126, v85 offset:42944
	ds_read_b128 v[122:125], v84 offset:16128
	v_add_f32_dpp v68, v68, v68 row_half_mirror row_mask:0xf bank_mask:0xf bound_ctrl:1
	ds_read_b128 v[110:113], v84 offset:40704
	ds_read_b128 v[114:117], v84 offset:24320
	v_add_f32_dpp v68, v68, v68 row_ror:8 row_mask:0xf bank_mask:0xf bound_ctrl:1
	v_pk_fma_f32 v[78:79], v[32:33], v[68:69], v[74:75] op_sel_hi:[1,0,1] neg_lo:[0,1,0] neg_hi:[0,1,0]
	v_pk_fma_f32 v[80:81], v[34:35], v[68:69], v[76:77] op_sel_hi:[1,0,1] neg_lo:[0,1,0] neg_hi:[0,1,0]
	s_waitcnt lgkmcnt(6)
	v_pk_mul_f32 v[68:69], v[46:47], v[78:79] op_sel_hi:[1,0]
	v_pk_mul_f32 v[70:71], v[66:67], v[58:59] op_sel_hi:[0,1]
	v_pk_fma_f32 v[68:69], v[48:49], v[78:79], v[68:69] op_sel:[0,1,0]
	v_pk_mul_f32 v[72:73], v[66:67], v[60:61] op_sel_hi:[0,1]
	v_pk_fma_f32 v[68:69], v[62:63], v[80:81], v[68:69] op_sel_hi:[1,0,1]
	v_pk_fma_f32 v[74:75], v[50:51], v[78:79], v[70:71]
	v_pk_fma_f32 v[68:69], v[64:65], v[80:81], v[68:69] op_sel:[0,1,0]
	v_pk_fma_f32 v[76:77], v[52:53], v[80:81], v[72:73]
	ds_read_b128 v[2:5], v84 offset:0
	v_add_f32_dpp v68, v68, v68 quad_perm:[1,0,3,2] row_mask:0xf bank_mask:0xf bound_ctrl:1
	ds_read_b128 v[18:21], v84 offset:8192
	v_add_f32_dpp v88, v69, v69 row_ror:8 row_mask:0xf bank_mask:0xf bound_ctrl:1
	v_add_f32_dpp v68, v68, v68 quad_perm:[2,3,0,1] row_mask:0xf bank_mask:0xf bound_ctrl:1
	ds_write2st64_b32 v86, v82, v88 offset0:56 offset1:58
	s_nop 0
	v_add_f32_dpp v68, v68, v68 row_half_mirror row_mask:0xf bank_mask:0xf bound_ctrl:1
	s_nop 1
	v_add_f32_dpp v68, v68, v68 row_ror:8 row_mask:0xf bank_mask:0xf bound_ctrl:1
	v_pk_fma_f32 v[78:79], v[54:55], v[68:69], v[74:75] op_sel_hi:[1,0,1] neg_lo:[0,1,0] neg_hi:[0,1,0]
	v_pk_fma_f32 v[80:81], v[56:57], v[68:69], v[76:77] op_sel_hi:[1,0,1] neg_lo:[0,1,0] neg_hi:[0,1,0]
	s_waitcnt lgkmcnt(3)
	v_pk_mul_f32 v[68:69], v[106:107], v[78:79] op_sel_hi:[1,0]
	v_pk_mul_f32 v[70:71], v[126:127], v[118:119] op_sel_hi:[0,1]
	v_pk_fma_f32 v[68:69], v[108:109], v[78:79], v[68:69] op_sel:[0,1,0]
	v_pk_mul_f32 v[72:73], v[126:127], v[120:121] op_sel_hi:[0,1]
	v_pk_fma_f32 v[68:69], v[122:123], v[80:81], v[68:69] op_sel_hi:[1,0,1]
	v_pk_fma_f32 v[74:75], v[110:111], v[78:79], v[70:71]
	v_pk_fma_f32 v[68:69], v[124:125], v[80:81], v[68:69] op_sel:[0,1,0]
	v_pk_fma_f32 v[76:77], v[112:113], v[80:81], v[72:73]
	s_nop 0
	v_add_f32_dpp v68, v68, v68 quad_perm:[1,0,3,2] row_mask:0xf bank_mask:0xf bound_ctrl:1
	s_nop 0
	v_add_f32_dpp v82, v69, v69 row_ror:8 row_mask:0xf bank_mask:0xf bound_ctrl:1
	v_add_f32_dpp v68, v68, v68 quad_perm:[2,3,0,1] row_mask:0xf bank_mask:0xf bound_ctrl:1
	s_nop 1
	v_add_f32_dpp v68, v68, v68 row_half_mirror row_mask:0xf bank_mask:0xf bound_ctrl:1
	s_nop 1
	v_add_f32_dpp v68, v68, v68 row_ror:8 row_mask:0xf bank_mask:0xf bound_ctrl:1
	v_pk_fma_f32 v[78:79], v[114:115], v[68:69], v[74:75] op_sel_hi:[1,0,1] neg_lo:[0,1,0] neg_hi:[0,1,0]
	v_pk_fma_f32 v[80:81], v[116:117], v[68:69], v[76:77] op_sel_hi:[1,0,1] neg_lo:[0,1,0] neg_hi:[0,1,0]
	s_waitcnt lgkmcnt(0)
	v_mul_f32_e32 v88, v3, v78
	v_fmac_f32_e32 v88, v5, v79
	v_fmac_f32_e32 v88, v19, v80
	v_fmac_f32_e32 v88, v21, v81
	s_nop 1
	v_add_f32_dpp v88, v88, v88 row_ror:8 row_mask:0xf bank_mask:0xf bound_ctrl:1
	ds_write2st64_b32 v86, v82, v88 offset0:60 offset1:62
	v_add_u32_e32 v101, 1, v101
.LBB0_623:
	s_andn2_saveexec_b64 s[92:93], s[14:15]
	s_cbranch_execz .LBB0_618
	s_waitcnt vmcnt(0) lgkmcnt(0)
	s_movk_i32 s0, 0x107
	v_add_u32_e32 v64, 1, v101
	v_cmp_ne_u32_e64 s[14:15], s0, v101
	s_and_saveexec_b64 s[16:17], s[14:15]
	s_cbranch_execz .Lscan_stage_done
	v_pk_mul_f32 v[60:61], v[42:43], v[34:35]
	v_pk_mul_f32 v[58:59], v[44:45], v[36:37]
	v_pk_mul_f32 v[66:67], v[60:61], v[60:61]
	v_pk_mul_f32 v[62:63], v[58:59], v[58:59]
	v_add_f32_e32 v0, v66, v67
	v_add_f32_e32 v0, v62, v0
	v_add_f32_e32 v0, v63, v0
	v_and_b32_e32 v63, 1, v64
	v_lshlrev_b32_e32 v70, 16, v111
	v_add_f32_dpp v0, v0, v0 quad_perm:[1,0,3,2] row_mask:0xf bank_mask:0xf bound_ctrl:1
	v_and_b32_e32 v71, 0xffff0000, v111
	v_lshlrev_b32_e32 v74, 16, v112
	v_add_f32_dpp v0, v0, v0 quad_perm:[2,3,0,1] row_mask:0xf bank_mask:0xf bound_ctrl:1
	v_and_b32_e32 v75, 0xffff0000, v112
	v_lshlrev_b32_e32 v76, 16, v113
	v_add_f32_dpp v0, v0, v0 row_half_mirror row_mask:0xf bank_mask:0xf bound_ctrl:1
	v_and_b32_e32 v77, 0xffff0000, v113
	s_nop 0
	v_add_f32_dpp v0, v0, v0 row_ror:8 row_mask:0xf bank_mask:0xf bound_ctrl:1
	v_mul_f32_e32 v62, 0x4f800000, v0
	v_cmp_gt_f32_e32 vcc, s74, v0
	s_nop 1
	v_cndmask_b32_e32 v0, v0, v62, vcc
	v_sqrt_f32_e32 v62, v0
	s_nop 0
	v_add_u32_e32 v65, -1, v62
	v_fma_f32 v66, -v65, v62, v0
	v_cmp_ge_f32_e64 s[14:15], 0, v66
	v_add_u32_e32 v66, 1, v62
	s_nop 0
	v_cndmask_b32_e64 v65, v62, v65, s[14:15]
	v_fma_f32 v62, -v66, v62, v0
	v_cmp_lt_f32_e64 s[14:15], 0, v62
	s_nop 1
	v_cndmask_b32_e64 v62, v65, v66, s[14:15]
	v_mul_f32_e32 v65, 0x37800000, v62
	v_cndmask_b32_e32 v62, v62, v65, vcc
	v_cmp_class_f32_e32 vcc, v0, v163
	s_nop 1
	v_cndmask_b32_e32 v0, v62, v0, vcc
	v_max_f32_e32 v62, 0x2b8cbccc, v0
	v_div_scale_f32 v65, s[0:1], v62, v62, 1.0
	v_rcp_f32_e32 v66, v65
	v_cmp_eq_u32_e32 vcc, 1, v63
	v_fma_f32 v63, -v65, v66, 1.0
	s_nop 0
	v_cndmask_b32_e32 v0, 0, v167, vcc
	v_fmac_f32_e32 v66, v63, v66
	v_div_scale_f32 v63, vcc, 1.0, v62, 1.0
	v_mul_f32_e32 v67, v63, v66
	v_fma_f32 v68, -v65, v67, v63
	v_fmac_f32_e32 v67, v68, v66
	v_fma_f32 v63, -v65, v67, v63
	v_div_fmas_f32 v63, v63, v66, v67
	v_div_fixup_f32 v66, v63, v62, 1.0
	v_pk_mul_f32 v[62:63], v[58:59], v[66:67] op_sel_hi:[1,0]
	v_lshlrev_b32_e32 v58, 16, v110
	v_and_b32_e32 v59, 0xffff0000, v110
	v_pk_mul_f32 v[60:61], v[60:61], v[66:67] op_sel_hi:[1,0]
	v_pk_add_f32 v[66:67], v[70:71], -1.0 op_sel_hi:[1,0]
	v_pk_add_f32 v[68:69], v[58:59], -1.0 op_sel_hi:[1,0]
	v_pk_fma_f32 v[66:67], v[48:49], v[66:67], 1.0 op_sel_hi:[1,1,0]
	v_pk_fma_f32 v[72:73], v[46:47], v[68:69], 1.0 op_sel_hi:[1,1,0]
	v_add_u32_e32 v0, 0, v0
	v_pk_mul_f32 v[68:69], v[36:37], v[66:67]
	v_pk_mul_f32 v[66:67], v[34:35], v[72:73]
	v_pk_mul_f32 v[72:73], v[62:63], v[70:71]
	v_pk_mul_f32 v[70:71], v[60:61], v[58:59]
	v_lshlrev_b32_e32 v58, 2, v98
	v_add3_u32 v59, v0, v165, v58
	v_mov_b32_e32 v172, v60
	v_mov_b32_e32 v173, v74
	v_mov_b32_e32 v174, v61
	v_mov_b32_e32 v175, v75
	v_mov_b32_e32 v176, v62
	v_mov_b32_e32 v177, v76
	v_mov_b32_e32 v178, v63
	v_mov_b32_e32 v179, v77
	ds_write_b128 v59, v[172:175]
	ds_write_b128 v59, v[176:179] offset:8192
	ds_write_b128 v59, v[38:41] offset:32768
	ds_write_b128 v59, v[70:73] offset:16384
	ds_write_b128 v59, v[66:69] offset:24576
	s_and_saveexec_b64 s[0:1], s[10:11]
	s_cbranch_execz .LBB0_728
	v_lshlrev_b32_e32 v60, 16, v106
	v_and_b32_e32 v61, 0xffff0000, v106
	v_lshlrev_b32_e32 v62, 16, v107
	v_and_b32_e32 v63, 0xffff0000, v107
	v_add3_u32 v59, v0, v142, v58
	ds_write_b128 v59, v[60:63] offset:40960
.LBB0_728:
	s_or_b64 exec, exec, s[0:1]
	v_pk_mul_f32 v[66:67], v[42:43], v[50:51]
	v_pk_mul_f32 v[60:61], v[44:45], v[52:53]
	v_pk_mul_f32 v[68:69], v[66:67], v[66:67]
	v_pk_mul_f32 v[62:63], v[60:61], v[60:61]
	v_add_f32_e32 v59, v68, v69
	v_add_f32_e32 v59, v62, v59
	v_add_f32_e32 v59, v63, v59
	v_lshlrev_b32_e32 v70, 16, v114
	v_and_b32_e32 v71, 0xffff0000, v114
	v_add_f32_dpp v59, v59, v59 quad_perm:[1,0,3,2] row_mask:0xf bank_mask:0xf bound_ctrl:1
	v_lshlrev_b32_e32 v72, 16, v115
	v_and_b32_e32 v73, 0xffff0000, v115
	v_add_f32_dpp v59, v59, v59 quad_perm:[2,3,0,1] row_mask:0xf bank_mask:0xf bound_ctrl:1
	v_lshlrev_b32_e32 v76, 16, v117
	v_and_b32_e32 v77, 0xffff0000, v117
	v_add_f32_dpp v59, v59, v59 row_half_mirror row_mask:0xf bank_mask:0xf bound_ctrl:1
	s_nop 1
	v_add_f32_dpp v59, v59, v59 row_ror:8 row_mask:0xf bank_mask:0xf bound_ctrl:1
	v_mul_f32_e32 v62, 0x4f800000, v59
	v_cmp_gt_f32_e32 vcc, s74, v59
	s_nop 1
	v_cndmask_b32_e32 v59, v59, v62, vcc
	v_sqrt_f32_e32 v62, v59
	s_nop 0
	v_add_u32_e32 v63, -1, v62
	v_fma_f32 v65, -v63, v62, v59
	v_cmp_ge_f32_e64 s[14:15], 0, v65
	v_add_u32_e32 v65, 1, v62
	s_nop 0
	v_cndmask_b32_e64 v63, v62, v63, s[14:15]
	v_fma_f32 v62, -v65, v62, v59
	v_cmp_lt_f32_e64 s[14:15], 0, v62
	s_nop 1
	v_cndmask_b32_e64 v62, v63, v65, s[14:15]
	v_mul_f32_e32 v63, 0x37800000, v62
	v_cndmask_b32_e32 v62, v62, v63, vcc
	v_cmp_class_f32_e32 vcc, v59, v163
	s_nop 1
	v_cndmask_b32_e32 v59, v62, v59, vcc
	v_max_f32_e32 v59, 0x2b8cbccc, v59
	v_div_scale_f32 v62, s[0:1], v59, v59, 1.0
	v_rcp_f32_e32 v63, v62
	s_nop 0
	v_fma_f32 v65, -v62, v63, 1.0
	v_fmac_f32_e32 v63, v65, v63
	v_div_scale_f32 v65, vcc, 1.0, v59, 1.0
	v_mul_f32_e32 v68, v65, v63
	v_fma_f32 v69, -v62, v68, v65
	v_fmac_f32_e32 v68, v69, v63
	v_fma_f32 v62, -v62, v68, v65
	v_div_fmas_f32 v62, v62, v63, v68
	v_div_fixup_f32 v68, v62, v59, 1.0
	v_pk_mul_f32 v[62:63], v[60:61], v[68:69] op_sel_hi:[1,0]
	v_pk_mul_f32 v[60:61], v[66:67], v[68:69] op_sel_hi:[1,0]
	v_pk_add_f32 v[66:67], v[72:73], -1.0 op_sel_hi:[1,0]
	v_pk_add_f32 v[68:69], v[70:71], -1.0 op_sel_hi:[1,0]
	v_lshlrev_b32_e32 v59, 2, v144
	v_pk_fma_f32 v[74:75], v[46:47], v[68:69], 1.0 op_sel_hi:[1,1,0]
	v_pk_fma_f32 v[66:67], v[48:49], v[66:67], 1.0 op_sel_hi:[1,1,0]
	v_add3_u32 v59, v0, v59, v58
	v_pk_mul_f32 v[68:69], v[52:53], v[66:67]
	v_pk_mul_f32 v[66:67], v[50:51], v[74:75]
	v_pk_mul_f32 v[72:73], v[62:63], v[72:73]
	v_pk_mul_f32 v[70:71], v[60:61], v[70:71]
	v_lshlrev_b32_e32 v74, 16, v116
	v_and_b32_e32 v75, 0xffff0000, v116
	v_mov_b32_e32 v172, v60
	v_mov_b32_e32 v173, v74
	v_mov_b32_e32 v174, v61
	v_mov_b32_e32 v175, v75
	v_mov_b32_e32 v176, v62
	v_mov_b32_e32 v177, v76
	v_mov_b32_e32 v178, v63
	v_mov_b32_e32 v179, v77
	ds_write_b128 v59, v[172:175]
	ds_write_b128 v59, v[176:179] offset:8192
	ds_write_b128 v59, v[54:57] offset:32768
	ds_write_b128 v59, v[70:73] offset:16384
	ds_write_b128 v59, v[66:69] offset:24576
	s_and_saveexec_b64 s[0:1], s[10:11]
	s_cbranch_execz .Lscan_stage_tail
	v_lshlrev_b32_e32 v60, 16, v108
	v_and_b32_e32 v61, 0xffff0000, v108
	v_lshlrev_b32_e32 v62, 16, v109
	v_and_b32_e32 v63, 0xffff0000, v109
	v_add3_u32 v0, v0, v144, v58
	ds_write_b128 v0, v[60:63] offset:40960
